# speedup vs baseline: 1.0346x; 1.0070x over previous
; __device__ __forceinline__ float silu_f(float x) { return x / (1.f + __expf(-x)); }
; __device__ __forceinline__ void prep_mod_job(const Params& p, int m, float* sm) {
;     ...
;   int l = m / 720, rem = m % 720;
;   int sg = rem / 144, cbk = rem % 144;
;   int col0 = cbk * 64;
;   float* sc = sm;
;   float* red = sm + 8192;
;   for (int e = tid; e < 8192; e += 256) {
;     int s = e >> 10, k = e & 1023;
;     int sidx = sg * 8 + s;
;     float c = sidx < 32 ? p.c_in[0][sidx * 1024 + k] : p.c_in[1][(sidx - 32) * 1024 + k];
;     sc[e] = silu_f(c);
;   }
.LBB0_82:
	s_mul_hi_i32 s4, s94, 0xb60b60b7
	s_add_i32 s4, s4, s94
	s_lshr_b32 s5, s4, 31
	s_ashr_i32 s10, s4, 9
	s_add_i32 s10, s10, s5
	s_mul_i32 s4, s10, 0x2d0
	s_sub_i32 s40, s94, s4
	s_mul_i32 s4, s40, 0xe39
	v_mov_b32_e32 v35, v197
	s_lshr_b32 s5, s4, 31
	s_ashr_i32 s11, s4, 19
	s_add_i32 s11, s11, s5
	v_lshl_add_u32 v36, v35, 2, s65
	s_lshl_b32 s56, s11, 3
	s_cmp_lt_i32 s56, 32
	s_cselect_b32 s6, s12, s14
	s_cselect_b32 s7, s13, s15
	s_cselect_b32 s8, 0, 32
	s_sub_i32 s8, s56, s8
	s_lshl_b32 s8, s8, 12
	s_add_u32 s6, s6, s8
	s_addc_u32 s7, s7, 0
	v_lshlrev_b32_e32 v2, 4, v35
	global_load_dwordx4 v[64:67], v2, s[6:7]
	v_add_u32_e32 v3, 0x1000, v2
	global_load_dwordx4 v[68:71], v3, s[6:7]
	v_add_u32_e32 v3, 0x2000, v2
	global_load_dwordx4 v[72:75], v3, s[6:7]
	v_add_u32_e32 v3, 0x3000, v2
	global_load_dwordx4 v[76:79], v3, s[6:7]
	v_add_u32_e32 v3, 0x4000, v2
	global_load_dwordx4 v[80:83], v3, s[6:7]
	v_add_u32_e32 v3, 0x5000, v2
	global_load_dwordx4 v[84:87], v3, s[6:7]
	v_add_u32_e32 v3, 0x6000, v2
	global_load_dwordx4 v[88:91], v3, s[6:7]
	v_add_u32_e32 v3, 0x7000, v2
	global_load_dwordx4 v[92:95], v3, s[6:7]
	v_add_u32_e32 v4, s65, v2
	s_waitcnt vmcnt(7)
	ds_write_b128 v4, v[64:67]
	s_waitcnt vmcnt(6)
	ds_write_b128 v4, v[68:71] offset:4096
	s_waitcnt vmcnt(5)
	ds_write_b128 v4, v[72:75] offset:8192
	s_waitcnt vmcnt(4)
	ds_write_b128 v4, v[76:79] offset:12288
	s_waitcnt vmcnt(3)
	ds_write_b128 v4, v[80:83] offset:16384
	s_waitcnt vmcnt(2)
	ds_write_b128 v4, v[84:87] offset:20480
	s_waitcnt vmcnt(1)
	ds_write_b128 v4, v[88:91] offset:24576
	s_waitcnt vmcnt(0)
	ds_write_b128 v4, v[92:95] offset:28672
	s_mov_b32 s6, 8
.Lms_loop:
	ds_read_b128 v[64:67], v4
	s_waitcnt lgkmcnt(0)
	v_mul_f32_e32 v3, 0xbfb8aa3b, v64
	v_exp_f32_e32 v3, v3
	s_nop 0
	v_add_f32_e32 v3, 1.0, v3
	v_div_scale_f32 v5, s[8:9], v3, v3, v64
	v_rcp_f32_e32 v7, v5
	v_div_scale_f32 v8, vcc, v64, v3, v64
	v_fma_f32 v9, -v5, v7, 1.0
	v_fmac_f32_e32 v7, v9, v7
	v_mul_f32_e32 v9, v8, v7
	v_fma_f32 v10, -v5, v9, v8
	v_fmac_f32_e32 v9, v10, v7
	v_fma_f32 v5, -v5, v9, v8
	v_div_fmas_f32 v5, v5, v7, v9
	v_div_fixup_f32 v64, v5, v3, v64
	v_mul_f32_e32 v3, 0xbfb8aa3b, v65
	v_exp_f32_e32 v3, v3
	s_nop 0
	v_add_f32_e32 v3, 1.0, v3
	v_div_scale_f32 v5, s[8:9], v3, v3, v65
	v_rcp_f32_e32 v7, v5
	v_div_scale_f32 v8, vcc, v65, v3, v65
	v_fma_f32 v9, -v5, v7, 1.0
	v_fmac_f32_e32 v7, v9, v7
	v_mul_f32_e32 v9, v8, v7
	v_fma_f32 v10, -v5, v9, v8
	v_fmac_f32_e32 v9, v10, v7
	v_fma_f32 v5, -v5, v9, v8
	v_div_fmas_f32 v5, v5, v7, v9
	v_div_fixup_f32 v65, v5, v3, v65
	v_mul_f32_e32 v3, 0xbfb8aa3b, v66
	v_exp_f32_e32 v3, v3
	s_nop 0
	v_add_f32_e32 v3, 1.0, v3
	v_div_scale_f32 v5, s[8:9], v3, v3, v66
	v_rcp_f32_e32 v7, v5
	v_div_scale_f32 v8, vcc, v66, v3, v66
	v_fma_f32 v9, -v5, v7, 1.0
	v_fmac_f32_e32 v7, v9, v7
	v_mul_f32_e32 v9, v8, v7
	v_fma_f32 v10, -v5, v9, v8
	v_fmac_f32_e32 v9, v10, v7
	v_fma_f32 v5, -v5, v9, v8
	v_div_fmas_f32 v5, v5, v7, v9
	v_div_fixup_f32 v66, v5, v3, v66
	v_mul_f32_e32 v3, 0xbfb8aa3b, v67
	v_exp_f32_e32 v3, v3
	s_nop 0
	v_add_f32_e32 v3, 1.0, v3
	v_div_scale_f32 v5, s[8:9], v3, v3, v67
	v_rcp_f32_e32 v7, v5
	v_div_scale_f32 v8, vcc, v67, v3, v67
	v_fma_f32 v9, -v5, v7, 1.0
	v_fmac_f32_e32 v7, v9, v7
	v_mul_f32_e32 v9, v8, v7
	v_fma_f32 v10, -v5, v9, v8
	v_fmac_f32_e32 v9, v10, v7
	v_fma_f32 v5, -v5, v9, v8
	v_div_fmas_f32 v5, v5, v7, v9
	v_div_fixup_f32 v67, v5, v3, v67
	ds_write_b128 v4, v[64:67]
	v_add_u32_e32 v4, 0x1000, v4
	s_add_i32 s6, s6, -1
	s_cmp_lg_u32 s6, 0
	s_cbranch_scc1 .Lms_loop
; __device__ __forceinline__ void prep_mod_job(const Params& p, int m, float* sm) {
;     ...
;   __syncthreads();
;   int col = tid & 63, kq = tid >> 6;
;   float acc[8];
; #pragma unroll
;   for (int s = 0; s < 8; ++s) acc[s] = 0.f;
;   const float* wp = p.ada_w + (size_t)l * 1024 * 9216 + (size_t)(kq * 256) * 9216 + col0 + col;
;   const float* scp = sc + kq * 256;
; #pragma unroll 8
;   for (int k = 0; k < 256; ++k) {
;     float w = wp[(size_t)k * 9216];
.LBB0_89:
	s_mul_i32 s4, s11, 0x90
	s_sub_i32 s4, s40, s4
	s_sext_i32_i16 s4, s4
	s_lshl_b32 s4, s4, 6
	s_mul_i32 s6, s10, 0x2400000
	s_mul_hi_i32 s5, s10, 0x2400000
	s_add_u32 s6, s16, s6
	v_ashrrev_i32_e32 v37, 6, v35
	s_addc_u32 s7, s17, s5
	v_lshlrev_b32_e32 v4, 8, v37
	v_mov_b64_e32 v[2:3], s[6:7]
	v_and_b32_e32 v16, 63, v35
	v_mad_i64_i32 v[2:3], s[6:7], v4, s87, v[2:3]
	s_ashr_i32 s5, s4, 31
	v_lshl_add_u64 v[2:3], s[4:5], 2, v[2:3]
	v_lshlrev_b32_e32 v14, 2, v16
	v_mov_b32_e32 v20, 0
	v_lshl_add_u64 v[18:19], v[2:3], 0, v[14:15]
	v_lshl_add_u32 v14, v37, 10, s65
	s_mov_b64 s[6:7], 0
	v_mov_b32_e32 v21, v20
	v_mov_b32_e32 v22, v20
	v_mov_b32_e32 v23, v20
	v_mov_b32_e32 v24, v20
	v_mov_b32_e32 v25, v20
	v_mov_b32_e32 v26, v20
	v_mov_b32_e32 v27, v20
	s_waitcnt lgkmcnt(0)
	s_barrier
	v_mov_b64_e32 v[2:3], v[18:19]
	s_mov_b64 s[6:7], 0x9000
	v_mov_b32_e32 v4, v14
	global_load_dword v64, v[2:3], off
	v_lshl_add_u64 v[2:3], v[2:3], 0, s[6:7]
	global_load_dword v65, v[2:3], off
	v_lshl_add_u64 v[2:3], v[2:3], 0, s[6:7]
	global_load_dword v66, v[2:3], off
	v_lshl_add_u64 v[2:3], v[2:3], 0, s[6:7]
	global_load_dword v67, v[2:3], off
	v_lshl_add_u64 v[2:3], v[2:3], 0, s[6:7]
	global_load_dword v68, v[2:3], off
	v_lshl_add_u64 v[2:3], v[2:3], 0, s[6:7]
	global_load_dword v69, v[2:3], off
	v_lshl_add_u64 v[2:3], v[2:3], 0, s[6:7]
	global_load_dword v70, v[2:3], off
	v_lshl_add_u64 v[2:3], v[2:3], 0, s[6:7]
	global_load_dword v71, v[2:3], off
	v_lshl_add_u64 v[2:3], v[2:3], 0, s[6:7]
	global_load_dword v72, v[2:3], off
	v_lshl_add_u64 v[2:3], v[2:3], 0, s[6:7]
	global_load_dword v73, v[2:3], off
	v_lshl_add_u64 v[2:3], v[2:3], 0, s[6:7]
	global_load_dword v74, v[2:3], off
	v_lshl_add_u64 v[2:3], v[2:3], 0, s[6:7]
	global_load_dword v75, v[2:3], off
	v_lshl_add_u64 v[2:3], v[2:3], 0, s[6:7]
	global_load_dword v76, v[2:3], off
	v_lshl_add_u64 v[2:3], v[2:3], 0, s[6:7]
	global_load_dword v77, v[2:3], off
	v_lshl_add_u64 v[2:3], v[2:3], 0, s[6:7]
	global_load_dword v78, v[2:3], off
	v_lshl_add_u64 v[2:3], v[2:3], 0, s[6:7]
	global_load_dword v79, v[2:3], off
	v_lshl_add_u64 v[2:3], v[2:3], 0, s[6:7]
	global_load_dword v80, v[2:3], off
	v_lshl_add_u64 v[2:3], v[2:3], 0, s[6:7]
	global_load_dword v81, v[2:3], off
	v_lshl_add_u64 v[2:3], v[2:3], 0, s[6:7]
	global_load_dword v82, v[2:3], off
	v_lshl_add_u64 v[2:3], v[2:3], 0, s[6:7]
	global_load_dword v83, v[2:3], off
	v_lshl_add_u64 v[2:3], v[2:3], 0, s[6:7]
	global_load_dword v84, v[2:3], off
	v_lshl_add_u64 v[2:3], v[2:3], 0, s[6:7]
	global_load_dword v85, v[2:3], off
	v_lshl_add_u64 v[2:3], v[2:3], 0, s[6:7]
	global_load_dword v86, v[2:3], off
	v_lshl_add_u64 v[2:3], v[2:3], 0, s[6:7]
	global_load_dword v87, v[2:3], off
	v_lshl_add_u64 v[2:3], v[2:3], 0, s[6:7]
	global_load_dword v88, v[2:3], off
	v_lshl_add_u64 v[2:3], v[2:3], 0, s[6:7]
	global_load_dword v89, v[2:3], off
	v_lshl_add_u64 v[2:3], v[2:3], 0, s[6:7]
	global_load_dword v90, v[2:3], off
	v_lshl_add_u64 v[2:3], v[2:3], 0, s[6:7]
	global_load_dword v91, v[2:3], off
	v_lshl_add_u64 v[2:3], v[2:3], 0, s[6:7]
	global_load_dword v92, v[2:3], off
	v_lshl_add_u64 v[2:3], v[2:3], 0, s[6:7]
	global_load_dword v93, v[2:3], off
	v_lshl_add_u64 v[2:3], v[2:3], 0, s[6:7]
	global_load_dword v94, v[2:3], off
	v_lshl_add_u64 v[2:3], v[2:3], 0, s[6:7]
	global_load_dword v95, v[2:3], off
	v_lshl_add_u64 v[2:3], v[2:3], 0, s[6:7]
	global_load_dword v96, v[2:3], off
	v_lshl_add_u64 v[2:3], v[2:3], 0, s[6:7]
	global_load_dword v97, v[2:3], off
	v_lshl_add_u64 v[2:3], v[2:3], 0, s[6:7]
	global_load_dword v98, v[2:3], off
	v_lshl_add_u64 v[2:3], v[2:3], 0, s[6:7]
	global_load_dword v99, v[2:3], off
	v_lshl_add_u64 v[2:3], v[2:3], 0, s[6:7]
	global_load_dword v100, v[2:3], off
	v_lshl_add_u64 v[2:3], v[2:3], 0, s[6:7]
	global_load_dword v101, v[2:3], off
	v_lshl_add_u64 v[2:3], v[2:3], 0, s[6:7]
	global_load_dword v102, v[2:3], off
	v_lshl_add_u64 v[2:3], v[2:3], 0, s[6:7]
	global_load_dword v103, v[2:3], off
	v_lshl_add_u64 v[2:3], v[2:3], 0, s[6:7]
	global_load_dword v104, v[2:3], off
	v_lshl_add_u64 v[2:3], v[2:3], 0, s[6:7]
	global_load_dword v105, v[2:3], off
	v_lshl_add_u64 v[2:3], v[2:3], 0, s[6:7]
	global_load_dword v106, v[2:3], off
	v_lshl_add_u64 v[2:3], v[2:3], 0, s[6:7]
	global_load_dword v107, v[2:3], off
	v_lshl_add_u64 v[2:3], v[2:3], 0, s[6:7]
	global_load_dword v108, v[2:3], off
	v_lshl_add_u64 v[2:3], v[2:3], 0, s[6:7]
	global_load_dword v109, v[2:3], off
	v_lshl_add_u64 v[2:3], v[2:3], 0, s[6:7]
	global_load_dword v110, v[2:3], off
	v_lshl_add_u64 v[2:3], v[2:3], 0, s[6:7]
	global_load_dword v111, v[2:3], off
	v_lshl_add_u64 v[2:3], v[2:3], 0, s[6:7]
	s_mov_b32 vcc_lo, 4

; __global__ void __launch_bounds__(NTHREADS, 2) fwd_megakernel(Params p_arg) {
;     ...
;         case 10: {
;           PRE();
;           ea.out16 = (u16*)(p.big + B_H); ea.rev = 1;
;           ea.rss_in = rssb + TH; ea.sw_in = swb + SW_F2 + (size_t)layer * 40 * 5632; ea.sw_ld = 5632;
;           phase_gemm<0>(xg2, DM, wl + O_W2, DM, DM, TH / 256, 5632 / 256, ea, bid, nb, smem);
.LBB0_130:
	v_readlane_b32 s0, v255, 7
	s_mov_b32 s6, s0
	s_mov_b32 s8, s1
	v_readlane_b32 s66, v255, 8
	s_cmp_eq_u32 s6, 0
	v_writelane_b32 v255, s1, 12
	s_cselect_b64 s[0:1], -1, 0
	v_writelane_b32 v255, s0, 13
	s_and_b64 s[2:3], s[0:1], exec
	s_cselect_b32 s93, 11, 13
	v_writelane_b32 v255, s1, 14
	s_cselect_b32 s0, 0, 32
	s_cmp_eq_u32 s66, 0
	v_writelane_b32 v254, s0, 2
	s_cselect_b64 s[0:1], -1, 0
	v_writelane_b32 v255, s0, 15
	s_mov_b64 s[2:3], -1
	s_cmp_lt_i32 s8, 5
	v_writelane_b32 v255, s1, 16
	s_mov_b32 s0, s6
	v_writelane_b32 v255, s0, 17
	s_nop 1
	v_writelane_b32 v255, s1, 18
	s_mul_i32 s0, s6, 6
	v_writelane_b32 v255, s0, 19
	s_mov_b64 s[6:7], 0
	s_nop 0
	v_writelane_b32 v255, s1, 20
	v_writelane_b32 v255, s8, 21
	s_mov_b64 s[0:1], 0
	v_writelane_b32 v255, s0, 22
	s_nop 1
	v_writelane_b32 v255, s1, 23
	v_writelane_b32 v255, s93, 24
	s_cbranch_scc1 .LBB0_411
	v_readlane_b32 s0, v255, 21
	s_cmp_gt_i32 s0, 7
	v_writelane_b32 v254, s66, 4
	s_cbranch_scc0 .LBB0_170
	s_cmp_gt_i32 s0, 8
	s_cbranch_scc0 .LBB0_171
	s_mov_b64 s[2:3], 0
	s_cmp_gt_i32 s0, 9
	s_mov_b64 s[0:1], 0
	s_cbranch_scc0 .LBB0_172
	v_readlane_b32 s0, v255, 21
	s_cmp_eq_u32 s0, 10
	s_cbranch_scc0 .LBB0_782
	v_readlane_b32 s8, v254, 11
	v_readlane_b32 s6, v254, 0
	v_readlane_b32 s9, v254, 12
	v_readlane_b32 s7, v254, 1
	s_andn2_b64 vcc, exec, s[8:9]
	s_cbranch_vccnz .LBB0_783
	v_readlane_b32 s0, v254, 4
	v_readlane_b32 s10, v255, 19
	s_mul_i32 s8, s0, 3
	v_readlane_b32 s11, v255, 20
	s_add_i32 s8, s10, s8
	s_load_dwordx2 s[10:11], s[6:7], 0xf8
	s_ashr_i32 s9, s8, 31
	s_lshl_b64 s[12:13], s[8:9], 18
	s_load_dwordx2 s[8:9], s[6:7], 0x118
	s_mul_i32 s7, s0, 0x27d8000
	s_mul_hi_i32 s6, s0, 0x27d8000
	s_waitcnt lgkmcnt(0)
	s_add_u32 s22, s10, s7
	s_addc_u32 s23, s11, s6
	s_add_u32 s6, s8, s12
	s_addc_u32 s7, s9, s13
	s_add_u32 s24, s8, 0x28000000
	s_addc_u32 s25, s9, 0
	s_add_u32 s68, s6, 0x27940000
	s_mul_i32 s15, s0, 0xdc000
	s_addc_u32 s69, s7, 0
	s_mul_hi_i32 s14, s0, 0xdc000
	s_add_u32 s6, s8, s15
	s_addc_u32 s7, s9, s14
	s_add_u32 s66, s6, 0x27cb4000
	s_addc_u32 s59, s7, 0
	s_add_u32 s28, s22, 0x1700000
	s_addc_u32 s29, s23, 0
	s_waitcnt vmcnt(0)
	v_mov_b32_e32 v148, 0
	s_mov_b64 s[16:17], -1
	v_readlane_b32 s30, v254, 26
	v_and_b32_e32 v230, 3, v223
	v_lshrrev_b32_e32 v224, 2, v223
	v_lshl_or_b32 v231, v230, 4, v224
	v_lshlrev_b32_e32 v231, 2, v231
	v_and_b32_e32 v250, 15, v223
	v_sub_u32_e32 v250, v224, v250
	v_mul_i32_i24_e32 v250, 0x1600, v250
	v_lshrrev_b32_e32 v251, 4, v223
	v_sub_u32_e32 v251, v230, v251
	v_lshl_add_u32 v250, v251, 3, v250
	v_ashrrev_i32_e32 v251, 31, v250
	s_branch .LBB0_138
; template <int EPI> ...
;     ...
;     if (EPI == 0) {
; #pragma unroll
;       for (int bj = 0; bj < 2; ++bj) {
;         const int cbase = bcol + bj * 128 + wc * 32;
;         float4 swg = make_float4(0.f, 0.f, 0.f, 0.f), swu = swg;
;         if (swrow) { swg = *(const float4*)(swrow + cbase + fq * 4); swu = *(const float4*)(swrow + cbase + 16 + fq * 4); }
;         const float sg4[4] = {swg.x, swg.y, swg.z, swg.w}, su4[4] = {swu.x, swu.y, swu.z, swu.w};
; #pragma unroll
;         for (int m = 0; m < 4; ++m) {
;           float v[4];
; #pragma unroll
;           for (int j = 0; j < 4; ++j) {
;             float g = acc[ai][bj][m][0][j] * rs[m] + sg4[j];
;             float u = acc[ai][bj][m][1][j] * rs[m] + su4[j];
;             v[j] = g * __builtin_amdgcn_rcpf(1.f + __expf(-g)) * u;
;           }
;           uint2 o; o.x = pack2(v[0], v[1]); o.y = pack2(v[2], v[3]);
;           *(uint2*)(ea.out16 + (size_t)(rb + m * 16 + fr) * DFF + (cbase >> 1) + fq * 4) = o;
;         }
;       }
.LBB0_137:
	v_mov_b32_e32 v42, v76
	v_mov_b32_e32 v43, v76
	s_waitcnt lgkmcnt(0)
	v_pk_fma_f32 v[28:29], v[28:29], v[42:43], v[62:63]
	v_pk_fma_f32 v[24:25], v[24:25], v[42:43], v[32:33]
	v_mul_f32_e32 v44, 0xbfb8aa3b, v28
	v_mul_f32_e32 v45, 0xbfb8aa3b, v29
	v_exp_f32_e32 v44, v44
	v_exp_f32_e32 v45, v45
	v_pk_fma_f32 v[26:27], v[26:27], v[42:43], v[34:35]
	v_mov_b32_e32 v76, v77
	v_add_f32_e32 v44, 1.0, v44
	v_add_f32_e32 v45, 1.0, v45
	v_rcp_f32_e32 v44, v44
	v_rcp_f32_e32 v45, v45
	v_pk_fma_f32 v[20:21], v[20:21], v[76:77], v[62:63]
	v_pk_fma_f32 v[16:17], v[16:17], v[76:77], v[32:33]
	v_pk_fma_f32 v[18:19], v[18:19], v[76:77], v[34:35]
	v_pk_mul_f32 v[28:29], v[28:29], v[44:45]
	v_mov_b32_e32 v38, v74
	v_pk_mul_f32 v[24:25], v[24:25], v[28:29]
	v_pk_fma_f32 v[28:29], v[30:31], v[42:43], v[64:65]
	v_cvt_pk_bf16_f32 v24, v24, v25
	v_mul_f32_e32 v25, 0xbfb8aa3b, v28
	v_exp_f32_e32 v25, v25
	v_mov_b32_e32 v39, v74
	v_pk_fma_f32 v[12:13], v[12:13], v[38:39], v[62:63]
	v_pk_fma_f32 v[8:9], v[8:9], v[38:39], v[32:33]
	v_add_f32_e32 v25, 1.0, v25
	v_rcp_f32_e32 v30, v25
	v_mul_f32_e32 v25, 0xbfb8aa3b, v29
	v_exp_f32_e32 v25, v25
	v_pk_fma_f32 v[10:11], v[10:11], v[38:39], v[34:35]
	v_mov_b32_e32 v74, v75
	v_pk_fma_f32 v[4:5], v[4:5], v[74:75], v[62:63]
	v_add_f32_e32 v25, 1.0, v25
	v_rcp_f32_e32 v31, v25
	v_pk_fma_f32 v[0:1], v[0:1], v[74:75], v[32:33]
	v_pk_fma_f32 v[2:3], v[2:3], v[74:75], v[34:35]
	s_and_b64 vcc, exec, s[12:13]
	v_pk_mul_f32 v[28:29], v[28:29], v[30:31]
	s_nop 0
	v_pk_mul_f32 v[26:27], v[26:27], v[28:29]
	s_nop 0
	v_cvt_pk_bf16_f32 v25, v26, v27
	v_lshl_add_u64 v[26:27], v[56:57], 0, s[16:17]
	v_lshl_add_u64 v[26:27], v[26:27], 0, v[198:199]
	ds_bpermute_b32 v228, v231, v24
	ds_bpermute_b32 v229, v231, v25
	v_lshl_add_u64 v[252:253], v[26:27], 0, v[250:251]
	s_waitcnt lgkmcnt(0)
	global_store_dwordx2 v[252:253], v[228:229], off
	v_mul_f32_e32 v24, 0xbfb8aa3b, v20
	v_mul_f32_e32 v25, 0xbfb8aa3b, v21
	v_exp_f32_e32 v24, v24
	v_exp_f32_e32 v25, v25
	v_add_f32_e32 v24, 1.0, v24
	v_add_f32_e32 v25, 1.0, v25
	v_rcp_f32_e32 v24, v24
	v_rcp_f32_e32 v25, v25
	s_nop 0
	v_pk_mul_f32 v[20:21], v[20:21], v[24:25]
	s_nop 0
	v_pk_mul_f32 v[16:17], v[16:17], v[20:21]
	v_pk_fma_f32 v[20:21], v[22:23], v[76:77], v[64:65]
	v_cvt_pk_bf16_f32 v16, v16, v17
	v_mul_f32_e32 v17, 0xbfb8aa3b, v20
	v_exp_f32_e32 v17, v17
	s_nop 0
	v_add_f32_e32 v17, 1.0, v17
	v_rcp_f32_e32 v22, v17
	v_mul_f32_e32 v17, 0xbfb8aa3b, v21
	v_exp_f32_e32 v17, v17
	s_nop 0
	v_add_f32_e32 v17, 1.0, v17
	v_rcp_f32_e32 v23, v17
	s_nop 0
	v_pk_mul_f32 v[20:21], v[20:21], v[22:23]
	s_nop 0
	v_pk_mul_f32 v[18:19], v[18:19], v[20:21]
	s_nop 0
	v_cvt_pk_bf16_f32 v17, v18, v19
	v_lshl_add_u64 v[18:19], v[48:49], 0, s[16:17]
	v_lshl_add_u64 v[18:19], v[18:19], 0, v[198:199]
	ds_bpermute_b32 v228, v231, v16
	ds_bpermute_b32 v229, v231, v17
	v_lshl_add_u64 v[252:253], v[18:19], 0, v[250:251]
	s_waitcnt lgkmcnt(0)
	global_store_dwordx2 v[252:253], v[228:229], off
	v_mul_f32_e32 v16, 0xbfb8aa3b, v12
	v_mul_f32_e32 v17, 0xbfb8aa3b, v13
	v_exp_f32_e32 v16, v16
	v_exp_f32_e32 v17, v17
	v_add_f32_e32 v16, 1.0, v16
	v_add_f32_e32 v17, 1.0, v17
	v_rcp_f32_e32 v16, v16
	v_rcp_f32_e32 v17, v17
	s_nop 0
	v_pk_mul_f32 v[12:13], v[12:13], v[16:17]
	s_nop 0
	v_pk_mul_f32 v[8:9], v[8:9], v[12:13]
	v_pk_fma_f32 v[12:13], v[14:15], v[38:39], v[64:65]
	v_cvt_pk_bf16_f32 v8, v8, v9
	v_mul_f32_e32 v9, 0xbfb8aa3b, v12
	v_exp_f32_e32 v9, v9
	s_nop 0
	v_add_f32_e32 v9, 1.0, v9
	v_rcp_f32_e32 v14, v9
	v_mul_f32_e32 v9, 0xbfb8aa3b, v13
	v_exp_f32_e32 v9, v9
	s_nop 0
	v_add_f32_e32 v9, 1.0, v9
	v_rcp_f32_e32 v15, v9
	s_nop 0
	v_pk_mul_f32 v[12:13], v[12:13], v[14:15]
	s_nop 0
	v_pk_mul_f32 v[10:11], v[10:11], v[12:13]
	s_nop 0
	v_cvt_pk_bf16_f32 v9, v10, v11
	v_lshl_add_u64 v[10:11], v[40:41], 0, s[16:17]
	v_lshl_add_u64 v[10:11], v[10:11], 0, v[198:199]
	ds_bpermute_b32 v228, v231, v8
	ds_bpermute_b32 v229, v231, v9
	v_lshl_add_u64 v[252:253], v[10:11], 0, v[250:251]
	s_waitcnt lgkmcnt(0)
	global_store_dwordx2 v[252:253], v[228:229], off
	v_mul_f32_e32 v8, 0xbfb8aa3b, v4
	v_mul_f32_e32 v9, 0xbfb8aa3b, v5
	v_exp_f32_e32 v8, v8
	v_exp_f32_e32 v9, v9
	v_add_f32_e32 v8, 1.0, v8
	v_add_f32_e32 v9, 1.0, v9
	v_rcp_f32_e32 v8, v8
	v_rcp_f32_e32 v9, v9
	s_nop 0
	v_pk_mul_f32 v[4:5], v[4:5], v[8:9]
	s_nop 0
	v_pk_mul_f32 v[0:1], v[0:1], v[4:5]
	v_pk_fma_f32 v[4:5], v[6:7], v[74:75], v[64:65]
	v_cvt_pk_bf16_f32 v0, v0, v1
	v_mul_f32_e32 v1, 0xbfb8aa3b, v4
	v_exp_f32_e32 v1, v1
	s_nop 0
	v_add_f32_e32 v1, 1.0, v1
	v_rcp_f32_e32 v6, v1
	v_mul_f32_e32 v1, 0xbfb8aa3b, v5
	v_exp_f32_e32 v1, v1
	s_nop 0
	v_add_f32_e32 v1, 1.0, v1
	v_rcp_f32_e32 v7, v1
	s_nop 0
	v_pk_mul_f32 v[4:5], v[4:5], v[6:7]
	s_nop 0
	v_pk_mul_f32 v[2:3], v[2:3], v[4:5]
	s_nop 0
	v_cvt_pk_bf16_f32 v1, v2, v3
	v_lshl_add_u64 v[2:3], v[36:37], 0, s[16:17]
	v_lshl_add_u64 v[2:3], v[2:3], 0, v[198:199]
	s_mov_b64 s[16:17], 0
	ds_bpermute_b32 v228, v231, v0
	ds_bpermute_b32 v229, v231, v1
	v_lshl_add_u64 v[252:253], v[2:3], 0, v[250:251]
	s_waitcnt lgkmcnt(0)
	global_store_dwordx2 v[252:253], v[228:229], off
	s_cbranch_vccnz .LBB0_783

; template <int EPI> ...
;     ...
;     if (EPI == 0) {
; #pragma unroll
;       for (int bj = 0; bj < 2; ++bj) {
;         const int cbase = bcol + bj * 128 + wc * 32;
;         float4 swg = make_float4(0.f, 0.f, 0.f, 0.f), swu = swg;
;         if (swrow) { swg = *(const float4*)(swrow + cbase + fq * 4); swu = *(const float4*)(swrow + cbase + 16 + fq * 4); }
;         const float sg4[4] = {swg.x, swg.y, swg.z, swg.w}, su4[4] = {swu.x, swu.y, swu.z, swu.w};
; #pragma unroll
;         for (int m = 0; m < 4; ++m) {
;           float v[4];
; #pragma unroll
;           for (int j = 0; j < 4; ++j) {
;             float g = acc[ai][bj][m][0][j] * rs[m] + sg4[j];
;             float u = acc[ai][bj][m][1][j] * rs[m] + su4[j];
;             v[j] = g * __builtin_amdgcn_rcpf(1.f + __expf(-g)) * u;
;           }
;           uint2 o; o.x = pack2(v[0], v[1]); o.y = pack2(v[2], v[3]);
;           *(uint2*)(ea.out16 + (size_t)(rb + m * 16 + fr) * DFF + (cbase >> 1) + fq * 4) = o;
;         }
;       }
.LBB0_164:
	s_lshl_b32 s15, s15, 6
	v_or_b32_e32 v88, s14, v141
	v_add_u32_e32 v150, s15, v88
	s_waitcnt lgkmcnt(0)
	v_pk_fma_f32 v[88:89], v[136:137], v[146:147], v[124:125] op_sel_hi:[1,0,1]
	v_pk_fma_f32 v[132:133], v[132:133], v[146:147], v[128:129] op_sel_hi:[1,0,1]
	v_mul_f32_e32 v91, 0xbfb8aa3b, v88
	v_exp_f32_e32 v91, v91
	v_pk_fma_f32 v[120:121], v[120:121], v[144:145], v[124:125] op_sel_hi:[1,0,1]
	v_pk_fma_f32 v[134:135], v[134:135], v[146:147], v[130:131] op_sel_hi:[1,0,1]
	s_ashr_i32 s14, s18, 1
	v_add_f32_e32 v91, 1.0, v91
	v_rcp_f32_e32 v136, v91
	v_mul_f32_e32 v91, 0xbfb8aa3b, v89
	v_exp_f32_e32 v91, v91
	s_ashr_i32 s15, s14, 31
	s_lshl_b64 s[14:15], s[14:15], 1
	v_lshlrev_b32_e32 v198, 1, v149
	v_add_f32_e32 v91, 1.0, v91
	v_rcp_f32_e32 v137, v91
	v_pk_fma_f32 v[116:117], v[116:117], v[144:145], v[128:129] op_sel_hi:[1,0,1]
	v_pk_fma_f32 v[118:119], v[118:119], v[144:145], v[130:131] op_sel_hi:[1,0,1]
	v_pk_fma_f32 v[112:113], v[112:113], v[142:143], v[124:125] op_sel_hi:[1,0,1]
	v_pk_mul_f32 v[88:89], v[88:89], v[136:137]
	v_pk_fma_f32 v[108:109], v[108:109], v[142:143], v[128:129] op_sel_hi:[1,0,1]
	v_pk_mul_f32 v[88:89], v[132:133], v[88:89]
	v_pk_fma_f32 v[110:111], v[110:111], v[142:143], v[130:131] op_sel_hi:[1,0,1]
	v_cvt_pk_bf16_f32 v136, v88, v89
	v_pk_fma_f32 v[88:89], v[138:139], v[146:147], v[126:127] op_sel_hi:[1,0,1]
	v_pk_fma_f32 v[104:105], v[104:105], v[140:141], v[124:125] op_sel_hi:[1,0,1]
	v_mul_f32_e32 v91, 0xbfb8aa3b, v88
	v_exp_f32_e32 v91, v91
	v_pk_fma_f32 v[100:101], v[100:101], v[140:141], v[128:129] op_sel_hi:[1,0,1]
	v_pk_fma_f32 v[102:103], v[102:103], v[140:141], v[130:131] op_sel_hi:[1,0,1]
	s_and_b64 vcc, exec, s[6:7]
	v_add_f32_e32 v91, 1.0, v91
	v_rcp_f32_e32 v132, v91
	v_mul_f32_e32 v91, 0xbfb8aa3b, v89
	v_exp_f32_e32 v91, v91
	s_nop 0
	v_add_f32_e32 v91, 1.0, v91
	v_rcp_f32_e32 v133, v91
	v_mul_f32_e32 v91, 0xbfb8aa3b, v120
	v_exp_f32_e32 v91, v91
	v_pk_mul_f32 v[88:89], v[88:89], v[132:133]
	s_nop 0
	v_pk_mul_f32 v[88:89], v[134:135], v[88:89]
	v_add_f32_e32 v91, 1.0, v91
	v_cvt_pk_bf16_f32 v137, v88, v89
	v_mov_b64_e32 v[88:89], s[8:9]
	v_mad_i64_i32 v[132:133], s[16:17], v150, s60, v[88:89]
	v_lshl_add_u64 v[134:135], v[132:133], 0, s[14:15]
	v_lshl_add_u64 v[134:135], v[134:135], 0, v[198:199]
	ds_bpermute_b32 v228, v231, v136
	ds_bpermute_b32 v229, v231, v137
	v_lshl_add_u64 v[252:253], v[134:135], 0, v[250:251]
	s_waitcnt lgkmcnt(0)
	global_store_dwordx2 v[252:253], v[228:229], off
	v_rcp_f32_e32 v134, v91
	v_mul_f32_e32 v91, 0xbfb8aa3b, v121
	v_exp_f32_e32 v91, v91
	s_nop 0
	v_add_f32_e32 v91, 1.0, v91
	v_rcp_f32_e32 v135, v91
	s_nop 0
	v_pk_mul_f32 v[120:121], v[120:121], v[134:135]
	s_nop 0
	v_pk_mul_f32 v[116:117], v[116:117], v[120:121]
	s_nop 0
	v_cvt_pk_bf16_f32 v120, v116, v117
	v_pk_fma_f32 v[116:117], v[122:123], v[144:145], v[126:127] op_sel_hi:[1,0,1]
	s_nop 0
	v_mul_f32_e32 v91, 0xbfb8aa3b, v116
	v_exp_f32_e32 v91, v91
	s_nop 0
	v_add_f32_e32 v91, 1.0, v91
	v_rcp_f32_e32 v122, v91
	v_mul_f32_e32 v91, 0xbfb8aa3b, v117
	v_exp_f32_e32 v91, v91
	s_nop 0
	v_add_f32_e32 v91, 1.0, v91
	v_rcp_f32_e32 v123, v91
	v_or_b32_e32 v91, 16, v150
	v_pk_mul_f32 v[116:117], v[116:117], v[122:123]
	s_nop 0
	v_pk_mul_f32 v[116:117], v[118:119], v[116:117]
	s_nop 0
	v_cvt_pk_bf16_f32 v121, v116, v117
	v_mad_i64_i32 v[116:117], s[16:17], v91, s60, v[88:89]
	v_mul_f32_e32 v91, 0xbfb8aa3b, v112
	v_exp_f32_e32 v91, v91
	v_lshl_add_u64 v[118:119], v[116:117], 0, s[14:15]
	v_lshl_add_u64 v[118:119], v[118:119], 0, v[198:199]
	ds_bpermute_b32 v228, v231, v120
	ds_bpermute_b32 v229, v231, v121
	v_lshl_add_u64 v[252:253], v[118:119], 0, v[250:251]
	s_waitcnt lgkmcnt(0)
	global_store_dwordx2 v[252:253], v[228:229], off
	v_add_f32_e32 v91, 1.0, v91
	v_rcp_f32_e32 v118, v91
	v_mul_f32_e32 v91, 0xbfb8aa3b, v113
	v_exp_f32_e32 v91, v91
	s_nop 0
	v_add_f32_e32 v91, 1.0, v91
	v_rcp_f32_e32 v119, v91
	s_nop 0
	v_pk_mul_f32 v[112:113], v[112:113], v[118:119]
	s_nop 0
	v_pk_mul_f32 v[108:109], v[108:109], v[112:113]
	s_nop 0
	v_cvt_pk_bf16_f32 v112, v108, v109
	v_pk_fma_f32 v[108:109], v[114:115], v[142:143], v[126:127] op_sel_hi:[1,0,1]
	s_nop 0
	v_mul_f32_e32 v91, 0xbfb8aa3b, v108
	v_exp_f32_e32 v91, v91
	s_nop 0
	v_add_f32_e32 v91, 1.0, v91
	v_rcp_f32_e32 v114, v91
	v_mul_f32_e32 v91, 0xbfb8aa3b, v109
	v_exp_f32_e32 v91, v91
	s_nop 0
	v_add_f32_e32 v91, 1.0, v91
	v_rcp_f32_e32 v115, v91
	v_or_b32_e32 v91, 32, v150
	v_pk_mul_f32 v[108:109], v[108:109], v[114:115]
	s_nop 0
	v_pk_mul_f32 v[108:109], v[110:111], v[108:109]
	s_nop 0
	v_cvt_pk_bf16_f32 v113, v108, v109
	v_mad_i64_i32 v[108:109], s[16:17], v91, s60, v[88:89]
	v_mul_f32_e32 v91, 0xbfb8aa3b, v104
	v_exp_f32_e32 v91, v91
	v_lshl_add_u64 v[110:111], v[108:109], 0, s[14:15]
	v_lshl_add_u64 v[110:111], v[110:111], 0, v[198:199]
	ds_bpermute_b32 v228, v231, v112
	ds_bpermute_b32 v229, v231, v113
	v_lshl_add_u64 v[252:253], v[110:111], 0, v[250:251]
	s_waitcnt lgkmcnt(0)
	global_store_dwordx2 v[252:253], v[228:229], off
	v_add_f32_e32 v91, 1.0, v91
	v_rcp_f32_e32 v110, v91
	v_mul_f32_e32 v91, 0xbfb8aa3b, v105
	v_exp_f32_e32 v91, v91
	s_nop 0
	v_add_f32_e32 v91, 1.0, v91
	v_rcp_f32_e32 v111, v91
	s_nop 0
	v_pk_mul_f32 v[104:105], v[104:105], v[110:111]
	s_nop 0
	v_pk_mul_f32 v[100:101], v[100:101], v[104:105]
	v_pk_fma_f32 v[104:105], v[106:107], v[140:141], v[126:127] op_sel_hi:[1,0,1]
	v_cvt_pk_bf16_f32 v100, v100, v101
	v_mul_f32_e32 v91, 0xbfb8aa3b, v104
	v_exp_f32_e32 v91, v91
	s_nop 0
	v_add_f32_e32 v91, 1.0, v91
	v_rcp_f32_e32 v106, v91
	v_mul_f32_e32 v91, 0xbfb8aa3b, v105
	v_exp_f32_e32 v91, v91
	s_nop 0
	v_add_f32_e32 v91, 1.0, v91
	v_rcp_f32_e32 v107, v91
	v_or_b32_e32 v91, 48, v150
	v_pk_mul_f32 v[104:105], v[104:105], v[106:107]
	s_nop 0
	v_pk_mul_f32 v[102:103], v[102:103], v[104:105]
	v_mad_i64_i32 v[104:105], s[16:17], v91, s60, v[88:89]
	v_lshl_add_u64 v[88:89], v[104:105], 0, s[14:15]
	v_cvt_pk_bf16_f32 v101, v102, v103
	v_lshl_add_u64 v[88:89], v[88:89], 0, v[198:199]
	ds_bpermute_b32 v228, v231, v100
	ds_bpermute_b32 v229, v231, v101
	v_lshl_add_u64 v[252:253], v[88:89], 0, v[250:251]
	s_waitcnt lgkmcnt(0)
	global_store_dwordx2 v[252:253], v[228:229], off
	v_mov_b32_e32 v91, 0
	v_mov_b32_e32 v88, 0
	v_mov_b32_e32 v89, 0
	v_mov_b32_e32 v102, 0
	v_mov_b32_e32 v103, 0
	v_mov_b32_e32 v100, 0
	v_mov_b32_e32 v101, 0
	s_cbranch_vccnz .LBB0_166
	s_lshl_b32 s16, s18, 2
	s_add_i32 s16, s19, s16
	v_lshl_add_u32 v100, v149, 2, s16
	ds_read_b128 v[88:91], v100 offset:512
	ds_read_b128 v[100:103], v100 offset:576
; template <int EPI> ...
;     ...
;     if (EPI == 0) {
; #pragma unroll
;       for (int bj = 0; bj < 2; ++bj) {
;         const int cbase = bcol + bj * 128 + wc * 32;
;         float4 swg = make_float4(0.f, 0.f, 0.f, 0.f), swu = swg;
;         if (swrow) { swg = *(const float4*)(swrow + cbase + fq * 4); swu = *(const float4*)(swrow + cbase + 16 + fq * 4); }
;         const float sg4[4] = {swg.x, swg.y, swg.z, swg.w}, su4[4] = {swu.x, swu.y, swu.z, swu.w};
; #pragma unroll
;         for (int m = 0; m < 4; ++m) {
;           float v[4];
; #pragma unroll
;           for (int j = 0; j < 4; ++j) {
;             float g = acc[ai][bj][m][0][j] * rs[m] + sg4[j];
;             float u = acc[ai][bj][m][1][j] * rs[m] + su4[j];
;             v[j] = g * __builtin_amdgcn_rcpf(1.f + __expf(-g)) * u;
;           }
;           uint2 o; o.x = pack2(v[0], v[1]); o.y = pack2(v[2], v[3]);
;           *(uint2*)(ea.out16 + (size_t)(rb + m * 16 + fr) * DFF + (cbase >> 1) + fq * 4) = o;
;         }
;       }
.LBB0_166:
	v_mov_b32_e32 v147, v146
	s_waitcnt lgkmcnt(0)
	v_pk_fma_f32 v[96:97], v[96:97], v[146:147], v[88:89]
	v_pk_fma_f32 v[92:93], v[92:93], v[146:147], v[100:101]
	v_mul_f32_e32 v106, 0xbfb8aa3b, v96
	v_mul_f32_e32 v107, 0xbfb8aa3b, v97
	v_exp_f32_e32 v106, v106
	v_exp_f32_e32 v107, v107
	s_or_b32 s16, s18, 0x80
	s_ashr_i32 s16, s16, 1
	v_add_f32_e32 v106, 1.0, v106
	v_add_f32_e32 v107, 1.0, v107
	v_rcp_f32_e32 v106, v106
	v_rcp_f32_e32 v107, v107
	s_ashr_i32 s17, s16, 31
	v_pk_fma_f32 v[94:95], v[94:95], v[146:147], v[102:103]
	s_lshl_b64 s[16:17], s[16:17], 1
	v_pk_mul_f32 v[96:97], v[96:97], v[106:107]
	v_mov_b32_e32 v145, v144
	v_pk_mul_f32 v[92:93], v[92:93], v[96:97]
	v_pk_fma_f32 v[96:97], v[98:99], v[146:147], v[90:91]
	v_cvt_pk_bf16_f32 v92, v92, v93
	v_mul_f32_e32 v93, 0xbfb8aa3b, v96
	v_exp_f32_e32 v93, v93
	v_pk_fma_f32 v[84:85], v[84:85], v[144:145], v[88:89]
	v_pk_fma_f32 v[80:81], v[80:81], v[144:145], v[100:101]
	v_pk_fma_f32 v[82:83], v[82:83], v[144:145], v[102:103]
	v_add_f32_e32 v93, 1.0, v93
	v_rcp_f32_e32 v98, v93
	v_mul_f32_e32 v93, 0xbfb8aa3b, v97
	v_exp_f32_e32 v93, v93
	v_mov_b32_e32 v143, v142
	v_pk_fma_f32 v[76:77], v[76:77], v[142:143], v[88:89]
	v_pk_fma_f32 v[72:73], v[72:73], v[142:143], v[100:101]
	v_add_f32_e32 v93, 1.0, v93
	v_rcp_f32_e32 v99, v93
	v_pk_fma_f32 v[74:75], v[74:75], v[142:143], v[102:103]
	v_mov_b32_e32 v141, v140
	v_pk_fma_f32 v[68:69], v[68:69], v[140:141], v[88:89]
	v_pk_mul_f32 v[96:97], v[96:97], v[98:99]
	v_pk_fma_f32 v[64:65], v[64:65], v[140:141], v[100:101]
	v_pk_mul_f32 v[94:95], v[94:95], v[96:97]
	v_pk_fma_f32 v[66:67], v[66:67], v[140:141], v[102:103]
	v_cvt_pk_bf16_f32 v93, v94, v95
	v_lshl_add_u64 v[94:95], v[132:133], 0, s[16:17]
	v_lshl_add_u64 v[94:95], v[94:95], 0, v[198:199]
	ds_bpermute_b32 v228, v231, v92
	ds_bpermute_b32 v229, v231, v93
	v_lshl_add_u64 v[252:253], v[94:95], 0, v[250:251]
	s_waitcnt lgkmcnt(0)
	global_store_dwordx2 v[252:253], v[228:229], off
	v_mul_f32_e32 v92, 0xbfb8aa3b, v84
	v_mul_f32_e32 v93, 0xbfb8aa3b, v85
	v_exp_f32_e32 v92, v92
	v_exp_f32_e32 v93, v93
	s_and_b64 vcc, exec, s[6:7]
	v_add_f32_e32 v92, 1.0, v92
	v_add_f32_e32 v93, 1.0, v93
	v_rcp_f32_e32 v92, v92
	v_rcp_f32_e32 v93, v93
	s_nop 0
	v_pk_mul_f32 v[84:85], v[84:85], v[92:93]
	s_nop 0
	v_pk_mul_f32 v[80:81], v[80:81], v[84:85]
	v_pk_fma_f32 v[84:85], v[86:87], v[144:145], v[90:91]
	v_cvt_pk_bf16_f32 v80, v80, v81
	v_mul_f32_e32 v81, 0xbfb8aa3b, v84
	v_exp_f32_e32 v81, v81
	s_nop 0
	v_add_f32_e32 v81, 1.0, v81
	v_rcp_f32_e32 v86, v81
	v_mul_f32_e32 v81, 0xbfb8aa3b, v85
	v_exp_f32_e32 v81, v81
	s_nop 0
	v_add_f32_e32 v81, 1.0, v81
	v_rcp_f32_e32 v87, v81
	s_nop 0
	v_pk_mul_f32 v[84:85], v[84:85], v[86:87]
	s_nop 0
	v_pk_mul_f32 v[82:83], v[82:83], v[84:85]
	s_nop 0
	v_cvt_pk_bf16_f32 v81, v82, v83
	v_lshl_add_u64 v[82:83], v[116:117], 0, s[16:17]
	v_lshl_add_u64 v[82:83], v[82:83], 0, v[198:199]
	ds_bpermute_b32 v228, v231, v80
	ds_bpermute_b32 v229, v231, v81
	v_lshl_add_u64 v[252:253], v[82:83], 0, v[250:251]
	s_waitcnt lgkmcnt(0)
	global_store_dwordx2 v[252:253], v[228:229], off
	v_mul_f32_e32 v80, 0xbfb8aa3b, v76
	v_mul_f32_e32 v81, 0xbfb8aa3b, v77
	v_exp_f32_e32 v80, v80
	v_exp_f32_e32 v81, v81
	v_add_f32_e32 v80, 1.0, v80
	v_add_f32_e32 v81, 1.0, v81
	v_rcp_f32_e32 v80, v80
	v_rcp_f32_e32 v81, v81
	s_nop 0
	v_pk_mul_f32 v[76:77], v[76:77], v[80:81]
	s_nop 0
	v_pk_mul_f32 v[72:73], v[72:73], v[76:77]
	v_pk_fma_f32 v[76:77], v[78:79], v[142:143], v[90:91]
	v_cvt_pk_bf16_f32 v72, v72, v73
	v_mul_f32_e32 v73, 0xbfb8aa3b, v76
	v_exp_f32_e32 v73, v73
	s_nop 0
	v_add_f32_e32 v73, 1.0, v73
	v_rcp_f32_e32 v78, v73
	v_mul_f32_e32 v73, 0xbfb8aa3b, v77
	v_exp_f32_e32 v73, v73
	s_nop 0
	v_add_f32_e32 v73, 1.0, v73
	v_rcp_f32_e32 v79, v73
	s_nop 0
	v_pk_mul_f32 v[76:77], v[76:77], v[78:79]
	s_nop 0
	v_pk_mul_f32 v[74:75], v[74:75], v[76:77]
	s_nop 0
	v_cvt_pk_bf16_f32 v73, v74, v75
	v_lshl_add_u64 v[74:75], v[108:109], 0, s[16:17]
	v_lshl_add_u64 v[74:75], v[74:75], 0, v[198:199]
	ds_bpermute_b32 v228, v231, v72
	ds_bpermute_b32 v229, v231, v73
	v_lshl_add_u64 v[252:253], v[74:75], 0, v[250:251]
	s_waitcnt lgkmcnt(0)
	global_store_dwordx2 v[252:253], v[228:229], off
	v_mul_f32_e32 v72, 0xbfb8aa3b, v68
	v_mul_f32_e32 v73, 0xbfb8aa3b, v69
	v_exp_f32_e32 v72, v72
	v_exp_f32_e32 v73, v73
	v_add_f32_e32 v72, 1.0, v72
	v_add_f32_e32 v73, 1.0, v73
	v_rcp_f32_e32 v72, v72
	v_rcp_f32_e32 v73, v73
	s_nop 0
	v_pk_mul_f32 v[68:69], v[68:69], v[72:73]
	s_nop 0
	v_pk_mul_f32 v[64:65], v[64:65], v[68:69]
	v_pk_fma_f32 v[68:69], v[70:71], v[140:141], v[90:91]
	v_cvt_pk_bf16_f32 v64, v64, v65
	v_mul_f32_e32 v65, 0xbfb8aa3b, v68
	v_exp_f32_e32 v65, v65
	v_mov_b32_e32 v72, 0
	v_mov_b32_e32 v73, 0
	v_add_f32_e32 v65, 1.0, v65
	v_rcp_f32_e32 v70, v65
	v_mul_f32_e32 v65, 0xbfb8aa3b, v69
	v_exp_f32_e32 v65, v65
	s_nop 0
	v_add_f32_e32 v65, 1.0, v65
	v_rcp_f32_e32 v71, v65
	s_nop 0
	v_pk_mul_f32 v[68:69], v[68:69], v[70:71]
	s_nop 0
	v_pk_mul_f32 v[66:67], v[66:67], v[68:69]
	v_mov_b32_e32 v68, 0
	v_cvt_pk_bf16_f32 v65, v66, v67
	v_lshl_add_u64 v[66:67], v[104:105], 0, s[16:17]
	v_lshl_add_u64 v[66:67], v[66:67], 0, v[198:199]
	ds_bpermute_b32 v228, v231, v64
	ds_bpermute_b32 v229, v231, v65
	v_lshl_add_u64 v[252:253], v[66:67], 0, v[250:251]
	s_waitcnt lgkmcnt(0)
	global_store_dwordx2 v[252:253], v[228:229], off
	ds_read2_b32 v[76:77], v151 offset0:128 offset1:144
	ds_read2_b32 v[74:75], v151 offset0:160 offset1:176
	v_mov_b32_e32 v64, 0
	v_mov_b32_e32 v69, 0
	v_mov_b32_e32 v66, 0
	v_mov_b32_e32 v67, 0
	v_mov_b32_e32 v70, 0
	v_mov_b32_e32 v71, 0
	s_cbranch_vccnz .LBB0_168
	s_lshl_b32 s20, s18, 2
	s_add_i32 s20, s19, s20
	v_lshl_add_u32 v65, v149, 2, s20
	ds_read_b128 v[66:69], v65
	ds_read_b128 v[70:73], v65 offset:64
; template <int EPI> ...
;     ...
;     if (EPI == 0) {
; #pragma unroll
;       for (int bj = 0; bj < 2; ++bj) {
;         const int cbase = bcol + bj * 128 + wc * 32;
;         float4 swg = make_float4(0.f, 0.f, 0.f, 0.f), swu = swg;
;         if (swrow) { swg = *(const float4*)(swrow + cbase + fq * 4); swu = *(const float4*)(swrow + cbase + 16 + fq * 4); }
;         const float sg4[4] = {swg.x, swg.y, swg.z, swg.w}, su4[4] = {swu.x, swu.y, swu.z, swu.w};
; #pragma unroll
;         for (int m = 0; m < 4; ++m) {
;           float v[4];
; #pragma unroll
;           for (int j = 0; j < 4; ++j) {
;             float g = acc[ai][bj][m][0][j] * rs[m] + sg4[j];
;             float u = acc[ai][bj][m][1][j] * rs[m] + su4[j];
;             v[j] = g * __builtin_amdgcn_rcpf(1.f + __expf(-g)) * u;
;           }
;           uint2 o; o.x = pack2(v[0], v[1]); o.y = pack2(v[2], v[3]);
;           *(uint2*)(ea.out16 + (size_t)(rb + m * 16 + fr) * DFF + (cbase >> 1) + fq * 4) = o;
;         }
;       }
.LBB0_168:
	s_waitcnt lgkmcnt(0)
	v_pk_fma_f32 v[60:61], v[60:61], v[76:77], v[66:67] op_sel_hi:[1,0,1]
	v_pk_fma_f32 v[56:57], v[56:57], v[76:77], v[70:71] op_sel_hi:[1,0,1]
	v_mul_f32_e32 v78, 0xbfb8aa3b, v60
	v_mul_f32_e32 v79, 0xbfb8aa3b, v61
	v_exp_f32_e32 v78, v78
	v_exp_f32_e32 v79, v79
	v_pk_fma_f32 v[58:59], v[58:59], v[76:77], v[72:73] op_sel_hi:[1,0,1]
	v_add_u32_e32 v65, 0x80, v150
	v_add_f32_e32 v78, 1.0, v78
	v_add_f32_e32 v79, 1.0, v79
	v_rcp_f32_e32 v78, v78
	v_rcp_f32_e32 v79, v79
	v_pk_fma_f32 v[44:45], v[44:45], v[74:75], v[66:67] op_sel_hi:[1,0,1]
	v_pk_fma_f32 v[40:41], v[40:41], v[74:75], v[70:71] op_sel_hi:[1,0,1]
	v_pk_fma_f32 v[42:43], v[42:43], v[74:75], v[72:73] op_sel_hi:[1,0,1]
	v_pk_mul_f32 v[60:61], v[60:61], v[78:79]
	s_and_b64 vcc, exec, s[6:7]
	v_pk_mul_f32 v[56:57], v[56:57], v[60:61]
	s_nop 0
	v_cvt_pk_bf16_f32 v60, v56, v57
	v_pk_fma_f32 v[56:57], v[62:63], v[76:77], v[68:69] op_sel_hi:[1,0,1]
	s_nop 0
	v_mul_f32_e32 v61, 0xbfb8aa3b, v56
	v_exp_f32_e32 v61, v61
	s_nop 0
	v_add_f32_e32 v61, 1.0, v61
	v_rcp_f32_e32 v62, v61
	v_mul_f32_e32 v61, 0xbfb8aa3b, v57
	v_exp_f32_e32 v61, v61
	s_nop 0
	v_add_f32_e32 v61, 1.0, v61
	v_rcp_f32_e32 v63, v61
	s_nop 0
	v_pk_mul_f32 v[56:57], v[56:57], v[62:63]
	s_nop 0
	v_pk_mul_f32 v[56:57], v[58:59], v[56:57]
	v_mov_b64_e32 v[58:59], s[8:9]
	v_cvt_pk_bf16_f32 v61, v56, v57
	v_mad_i64_i32 v[56:57], s[20:21], v65, s60, v[58:59]
	v_lshl_add_u64 v[62:63], v[56:57], 0, s[14:15]
	v_lshl_add_u64 v[62:63], v[62:63], 0, v[198:199]
	ds_bpermute_b32 v228, v231, v60
	ds_bpermute_b32 v229, v231, v61
	v_lshl_add_u64 v[252:253], v[62:63], 0, v[250:251]
	s_waitcnt lgkmcnt(0)
	global_store_dwordx2 v[252:253], v[228:229], off
	v_mov_b32_e32 v60, v77
	v_pk_fma_f32 v[52:53], v[52:53], v[60:61], v[66:67] op_sel_hi:[1,0,1]
	v_mov_b32_e32 v65, 0
	v_mul_f32_e32 v61, 0xbfb8aa3b, v52
	v_exp_f32_e32 v61, v61
	s_nop 0
	v_add_f32_e32 v61, 1.0, v61
	v_rcp_f32_e32 v62, v61
	v_pk_fma_f32 v[48:49], v[48:49], v[60:61], v[70:71] op_sel_hi:[1,0,1]
	v_mul_f32_e32 v61, 0xbfb8aa3b, v53
	v_exp_f32_e32 v61, v61
	s_nop 0
	v_add_f32_e32 v61, 1.0, v61
	v_rcp_f32_e32 v63, v61
	v_pk_fma_f32 v[50:51], v[50:51], v[60:61], v[72:73] op_sel_hi:[1,0,1]
	v_pk_mul_f32 v[52:53], v[52:53], v[62:63]
	s_nop 0
	v_pk_mul_f32 v[48:49], v[48:49], v[52:53]
	v_mov_b32_e32 v62, 0
	v_cvt_pk_bf16_f32 v52, v48, v49
	v_pk_fma_f32 v[48:49], v[54:55], v[60:61], v[68:69] op_sel_hi:[1,0,1]
	v_mov_b32_e32 v63, 0
	v_mul_f32_e32 v53, 0xbfb8aa3b, v48
	v_exp_f32_e32 v53, v53
	s_nop 0
	v_add_f32_e32 v53, 1.0, v53
	v_rcp_f32_e32 v54, v53
	v_mul_f32_e32 v53, 0xbfb8aa3b, v49
	v_exp_f32_e32 v53, v53
	s_nop 0
	v_add_f32_e32 v53, 1.0, v53
	v_rcp_f32_e32 v55, v53
	s_nop 0
	v_pk_mul_f32 v[48:49], v[48:49], v[54:55]
	s_nop 0
	v_pk_mul_f32 v[48:49], v[50:51], v[48:49]
	s_nop 0
	v_cvt_pk_bf16_f32 v53, v48, v49
	v_add_u32_e32 v48, 0x90, v150
	v_mad_i64_i32 v[48:49], s[20:21], v48, s60, v[58:59]
	v_lshl_add_u64 v[50:51], v[48:49], 0, s[14:15]
	v_lshl_add_u64 v[50:51], v[50:51], 0, v[198:199]
	ds_bpermute_b32 v228, v231, v52
	ds_bpermute_b32 v229, v231, v53
	v_lshl_add_u64 v[252:253], v[50:51], 0, v[250:251]
	s_waitcnt lgkmcnt(0)
	global_store_dwordx2 v[252:253], v[228:229], off
	v_mul_f32_e32 v50, 0xbfb8aa3b, v44
	v_mul_f32_e32 v51, 0xbfb8aa3b, v45
	v_exp_f32_e32 v50, v50
	v_exp_f32_e32 v51, v51
	v_add_f32_e32 v50, 1.0, v50
	v_add_f32_e32 v51, 1.0, v51
	v_rcp_f32_e32 v50, v50
	v_rcp_f32_e32 v51, v51
	s_nop 0
	v_pk_mul_f32 v[44:45], v[44:45], v[50:51]
	s_nop 0
	v_pk_mul_f32 v[40:41], v[40:41], v[44:45]
	s_nop 0
	v_cvt_pk_bf16_f32 v44, v40, v41
	v_pk_fma_f32 v[40:41], v[46:47], v[74:75], v[68:69] op_sel_hi:[1,0,1]
	s_nop 0
	v_mul_f32_e32 v45, 0xbfb8aa3b, v40
	v_exp_f32_e32 v45, v45
	s_nop 0
	v_add_f32_e32 v45, 1.0, v45
	v_rcp_f32_e32 v46, v45
	v_mul_f32_e32 v45, 0xbfb8aa3b, v41
	v_exp_f32_e32 v45, v45
	s_nop 0
	v_add_f32_e32 v45, 1.0, v45
	v_rcp_f32_e32 v47, v45
	s_nop 0
	v_pk_mul_f32 v[40:41], v[40:41], v[46:47]
	s_nop 0
	v_pk_mul_f32 v[40:41], v[42:43], v[40:41]
	s_nop 0
	v_cvt_pk_bf16_f32 v45, v40, v41
	v_add_u32_e32 v40, 0xa0, v150
	v_mad_i64_i32 v[40:41], s[20:21], v40, s60, v[58:59]
	v_lshl_add_u64 v[42:43], v[40:41], 0, s[14:15]
	v_lshl_add_u64 v[42:43], v[42:43], 0, v[198:199]
	ds_bpermute_b32 v228, v231, v44
	ds_bpermute_b32 v229, v231, v45
	v_lshl_add_u64 v[252:253], v[42:43], 0, v[250:251]
	s_waitcnt lgkmcnt(0)
	global_store_dwordx2 v[252:253], v[228:229], off
	v_mov_b32_e32 v42, v75
	v_pk_fma_f32 v[36:37], v[36:37], v[42:43], v[66:67] op_sel_hi:[1,0,1]
	s_nop 0
	v_mul_f32_e32 v43, 0xbfb8aa3b, v36
	v_exp_f32_e32 v43, v43
	s_nop 0
	v_add_f32_e32 v43, 1.0, v43
	v_rcp_f32_e32 v44, v43
	v_pk_fma_f32 v[32:33], v[32:33], v[42:43], v[70:71] op_sel_hi:[1,0,1]
	v_mul_f32_e32 v43, 0xbfb8aa3b, v37
	v_exp_f32_e32 v43, v43
	s_nop 0
	v_add_f32_e32 v43, 1.0, v43
	v_rcp_f32_e32 v45, v43
	v_pk_fma_f32 v[34:35], v[34:35], v[42:43], v[72:73] op_sel_hi:[1,0,1]
	v_pk_mul_f32 v[36:37], v[36:37], v[44:45]
	s_nop 0
	v_pk_mul_f32 v[32:33], v[32:33], v[36:37]
	v_pk_fma_f32 v[36:37], v[38:39], v[42:43], v[68:69] op_sel_hi:[1,0,1]
	v_cvt_pk_bf16_f32 v32, v32, v33
	v_mul_f32_e32 v33, 0xbfb8aa3b, v36
	v_exp_f32_e32 v33, v33
	s_nop 0
	v_add_f32_e32 v33, 1.0, v33
	v_rcp_f32_e32 v38, v33
	v_mul_f32_e32 v33, 0xbfb8aa3b, v37
	v_exp_f32_e32 v33, v33
	s_nop 0
	v_add_f32_e32 v33, 1.0, v33
	v_rcp_f32_e32 v39, v33
	s_nop 0
	v_pk_mul_f32 v[36:37], v[36:37], v[38:39]
	s_nop 0
	v_pk_mul_f32 v[34:35], v[34:35], v[36:37]
	s_nop 0
	v_cvt_pk_bf16_f32 v33, v34, v35
	v_add_u32_e32 v34, 0xb0, v150
	v_mad_i64_i32 v[36:37], s[20:21], v34, s60, v[58:59]
	v_lshl_add_u64 v[34:35], v[36:37], 0, s[14:15]
	v_lshl_add_u64 v[34:35], v[34:35], 0, v[198:199]
	ds_bpermute_b32 v228, v231, v32
	ds_bpermute_b32 v229, v231, v33
	v_lshl_add_u64 v[252:253], v[34:35], 0, v[250:251]
	s_waitcnt lgkmcnt(0)
	global_store_dwordx2 v[252:253], v[228:229], off
	v_mov_b32_e32 v34, 0
	v_mov_b32_e32 v35, 0
	v_mov_b32_e32 v32, 0
	v_mov_b32_e32 v33, 0
	s_cbranch_vccnz .LBB0_137
	s_lshl_b32 s6, s18, 2
	s_add_i32 s19, s19, s6
	v_lshl_add_u32 v32, v149, 2, s19
	ds_read_b128 v[62:65], v32 offset:512
	ds_read_b128 v[32:35], v32 offset:576
	s_branch .LBB0_137

; template <int EPI> ...
;     ...
;     if (EPI == 0) {
; #pragma unroll
;       for (int bj = 0; bj < 2; ++bj) {
;         const int cbase = bcol + bj * 128 + wc * 32;
;         float4 swg = make_float4(0.f, 0.f, 0.f, 0.f), swu = swg;
;         if (swrow) { swg = *(const float4*)(swrow + cbase + fq * 4); swu = *(const float4*)(swrow + cbase + 16 + fq * 4); }
;         const float sg4[4] = {swg.x, swg.y, swg.z, swg.w}, su4[4] = {swu.x, swu.y, swu.z, swu.w};
; #pragma unroll
;         for (int m = 0; m < 4; ++m) {
;           float v[4];
; #pragma unroll
;           for (int j = 0; j < 4; ++j) {
;             float g = acc[ai][bj][m][0][j] * rs[m] + sg4[j];
;             float u = acc[ai][bj][m][1][j] * rs[m] + su4[j];
;             v[j] = g * __builtin_amdgcn_rcpf(1.f + __expf(-g)) * u;
;           }
;           uint2 o; o.x = pack2(v[0], v[1]); o.y = pack2(v[2], v[3]);
;           *(uint2*)(ea.out16 + (size_t)(rb + m * 16 + fr) * DFF + (cbase >> 1) + fq * 4) = o;
;         }
;       }
; __global__ void __launch_bounds__(NTHREADS, 2) fwd_megakernel(Params p_arg) {
;     ...
;         case 1: {
;           PRE();
;           ea.out16 = (u16*)(p.big + B_H); ea.rev = layer;
;           if (layer == 1) { ea.rss_in = rssb - TH; ea.sw_in = swb + SW_F1; ea.sw_ld = 5632; }
;           phase_gemm<0>(p.xn, DM, wl + O_W1, DM, DM, TH / 256, 5632 / 256, ea, bid, nb, smem);
.LBB0_551:
	s_mov_b64 s[8:9], 0
	s_and_b64 vcc, exec, s[2:3]
	s_cbranch_vccz .LBB0_600
	v_readlane_b32 s0, v255, 21
	s_cmp_gt_i32 s0, 0
	s_mov_b64 s[2:3], -1
	s_cbranch_scc0 .LBB0_598
	v_readlane_b32 s6, v254, 11
	v_readlane_b32 s2, v254, 0
	v_readlane_b32 s7, v254, 12
	v_readlane_b32 s3, v254, 1
	s_andn2_b64 vcc, exec, s[6:7]
	s_cbranch_vccnz .LBB0_597
	s_load_dwordx2 s[6:7], s[2:3], 0xf8
	s_load_dwordx4 s[12:15], s[2:3], 0x110
	v_readlane_b32 s0, v255, 19
	s_mov_b32 s8, s0
	s_ashr_i32 s9, s0, 31
	s_lshl_b64 s[8:9], s[8:9], 18
	s_mul_i32 s3, s66, 0x27d8000
	s_mul_hi_i32 s2, s66, 0x27d8000
	s_waitcnt lgkmcnt(0)
	s_add_u32 s26, s6, s3
	s_addc_u32 s27, s7, s2
	s_add_u32 s2, s14, s8
	s_addc_u32 s3, s15, s9
	s_add_u32 s2, s2, 0x27980000
	v_readlane_b32 s1, v255, 20
	s_addc_u32 s3, s3, 0
	v_writelane_b32 v255, s0, 19
	s_add_u32 s28, s14, 0x27e6c000
	s_addc_u32 s29, s15, 0
	v_writelane_b32 v255, s1, 20
	s_waitcnt vmcnt(0)
	v_mov_b32_e32 v148, 0
	s_mov_b64 s[6:7], -1
	v_readlane_b32 s30, v254, 26
	v_and_b32_e32 v230, 3, v223
	v_lshrrev_b32_e32 v224, 2, v223
	v_lshl_or_b32 v231, v230, 4, v224
	v_lshlrev_b32_e32 v231, 2, v231
	v_and_b32_e32 v250, 15, v223
	v_sub_u32_e32 v250, v224, v250
	v_mul_i32_i24_e32 v250, 0x1600, v250
	v_lshrrev_b32_e32 v251, 4, v223
	v_sub_u32_e32 v251, v230, v251
	v_lshl_add_u32 v250, v251, 3, v250
	v_ashrrev_i32_e32 v251, 31, v250
	s_branch .LBB0_556
.LBB0_555:
	v_mov_b32_e32 v81, v80
	s_waitcnt lgkmcnt(0)
	v_pk_fma_f32 v[28:29], v[28:29], v[80:81], v[62:63]
	v_pk_fma_f32 v[24:25], v[24:25], v[80:81], v[32:33]
	v_mul_f32_e32 v38, 0xbfb8aa3b, v28
	v_mul_f32_e32 v39, 0xbfb8aa3b, v29
	v_exp_f32_e32 v38, v38
	v_exp_f32_e32 v39, v39
	v_pk_fma_f32 v[26:27], v[26:27], v[80:81], v[34:35]
	v_mov_b32_e32 v79, v78
	v_add_f32_e32 v38, 1.0, v38
	v_add_f32_e32 v39, 1.0, v39
	v_rcp_f32_e32 v38, v38
	v_rcp_f32_e32 v39, v39
	v_pk_fma_f32 v[20:21], v[20:21], v[78:79], v[62:63]
	v_pk_fma_f32 v[16:17], v[16:17], v[78:79], v[32:33]
	v_pk_fma_f32 v[18:19], v[18:19], v[78:79], v[34:35]
	v_pk_mul_f32 v[28:29], v[28:29], v[38:39]
	v_mov_b32_e32 v77, v76
	v_pk_mul_f32 v[24:25], v[24:25], v[28:29]
	v_pk_fma_f32 v[28:29], v[30:31], v[80:81], v[64:65]
	v_cvt_pk_bf16_f32 v24, v24, v25
	v_mul_f32_e32 v25, 0xbfb8aa3b, v28
	v_exp_f32_e32 v25, v25
	v_pk_fma_f32 v[12:13], v[12:13], v[76:77], v[62:63]
	v_pk_fma_f32 v[8:9], v[8:9], v[76:77], v[32:33]
	v_pk_fma_f32 v[10:11], v[10:11], v[76:77], v[34:35]
	v_add_f32_e32 v25, 1.0, v25
	v_rcp_f32_e32 v30, v25
	v_mul_f32_e32 v25, 0xbfb8aa3b, v29
	v_exp_f32_e32 v25, v25
	v_mov_b32_e32 v75, v74
	v_pk_fma_f32 v[4:5], v[4:5], v[74:75], v[62:63]
	v_pk_fma_f32 v[0:1], v[0:1], v[74:75], v[32:33]
	v_add_f32_e32 v25, 1.0, v25
	v_rcp_f32_e32 v31, v25
	v_pk_fma_f32 v[2:3], v[2:3], v[74:75], v[34:35]
	s_mov_b64 s[6:7], 0
	s_and_b64 vcc, exec, s[8:9]
	v_pk_mul_f32 v[28:29], v[28:29], v[30:31]
	s_nop 0
	v_pk_mul_f32 v[26:27], v[26:27], v[28:29]
	s_nop 0
	v_cvt_pk_bf16_f32 v25, v26, v27
	v_lshl_add_u64 v[26:27], v[56:57], 0, s[18:19]
	v_lshl_add_u64 v[26:27], v[26:27], 0, v[198:199]
	ds_bpermute_b32 v228, v231, v24
	ds_bpermute_b32 v229, v231, v25
	v_lshl_add_u64 v[252:253], v[26:27], 0, v[250:251]
	s_waitcnt lgkmcnt(0)
	global_store_dwordx2 v[252:253], v[228:229], off
	v_mul_f32_e32 v24, 0xbfb8aa3b, v20
	v_mul_f32_e32 v25, 0xbfb8aa3b, v21
	v_exp_f32_e32 v24, v24
	v_exp_f32_e32 v25, v25
	v_add_f32_e32 v24, 1.0, v24
	v_add_f32_e32 v25, 1.0, v25
	v_rcp_f32_e32 v24, v24
	v_rcp_f32_e32 v25, v25
	s_nop 0
	v_pk_mul_f32 v[20:21], v[20:21], v[24:25]
	s_nop 0
	v_pk_mul_f32 v[16:17], v[16:17], v[20:21]
	v_pk_fma_f32 v[20:21], v[22:23], v[78:79], v[64:65]
	v_cvt_pk_bf16_f32 v16, v16, v17
	v_mul_f32_e32 v17, 0xbfb8aa3b, v20
	v_exp_f32_e32 v17, v17
	s_nop 0
	v_add_f32_e32 v17, 1.0, v17
	v_rcp_f32_e32 v22, v17
	v_mul_f32_e32 v17, 0xbfb8aa3b, v21
	v_exp_f32_e32 v17, v17
	s_nop 0
	v_add_f32_e32 v17, 1.0, v17
	v_rcp_f32_e32 v23, v17
	s_nop 0
	v_pk_mul_f32 v[20:21], v[20:21], v[22:23]
	s_nop 0
	v_pk_mul_f32 v[18:19], v[18:19], v[20:21]
	s_nop 0
	v_cvt_pk_bf16_f32 v17, v18, v19
	v_lshl_add_u64 v[18:19], v[48:49], 0, s[18:19]
	v_lshl_add_u64 v[18:19], v[18:19], 0, v[198:199]
	ds_bpermute_b32 v228, v231, v16
	ds_bpermute_b32 v229, v231, v17
	v_lshl_add_u64 v[252:253], v[18:19], 0, v[250:251]
	s_waitcnt lgkmcnt(0)
	global_store_dwordx2 v[252:253], v[228:229], off
	v_mul_f32_e32 v16, 0xbfb8aa3b, v12
	v_mul_f32_e32 v17, 0xbfb8aa3b, v13
	v_exp_f32_e32 v16, v16
	v_exp_f32_e32 v17, v17
	v_add_f32_e32 v16, 1.0, v16
	v_add_f32_e32 v17, 1.0, v17
	v_rcp_f32_e32 v16, v16
	v_rcp_f32_e32 v17, v17
	s_nop 0
	v_pk_mul_f32 v[12:13], v[12:13], v[16:17]
	s_nop 0
	v_pk_mul_f32 v[8:9], v[8:9], v[12:13]
	v_pk_fma_f32 v[12:13], v[14:15], v[76:77], v[64:65]
	v_cvt_pk_bf16_f32 v8, v8, v9
	v_mul_f32_e32 v9, 0xbfb8aa3b, v12
	v_exp_f32_e32 v9, v9
	s_nop 0
	v_add_f32_e32 v9, 1.0, v9
	v_rcp_f32_e32 v14, v9
	v_mul_f32_e32 v9, 0xbfb8aa3b, v13
	v_exp_f32_e32 v9, v9
	s_nop 0
	v_add_f32_e32 v9, 1.0, v9
	v_rcp_f32_e32 v15, v9
	s_nop 0
	v_pk_mul_f32 v[12:13], v[12:13], v[14:15]
	s_nop 0
	v_pk_mul_f32 v[10:11], v[10:11], v[12:13]
	s_nop 0
	v_cvt_pk_bf16_f32 v9, v10, v11
	v_lshl_add_u64 v[10:11], v[40:41], 0, s[18:19]
	v_lshl_add_u64 v[10:11], v[10:11], 0, v[198:199]
	ds_bpermute_b32 v228, v231, v8
	ds_bpermute_b32 v229, v231, v9
	v_lshl_add_u64 v[252:253], v[10:11], 0, v[250:251]
	s_waitcnt lgkmcnt(0)
	global_store_dwordx2 v[252:253], v[228:229], off
	v_mul_f32_e32 v8, 0xbfb8aa3b, v4
	v_mul_f32_e32 v9, 0xbfb8aa3b, v5
	v_exp_f32_e32 v8, v8
	v_exp_f32_e32 v9, v9
	v_add_f32_e32 v8, 1.0, v8
	v_add_f32_e32 v9, 1.0, v9
	v_rcp_f32_e32 v8, v8
	v_rcp_f32_e32 v9, v9
	s_nop 0
	v_pk_mul_f32 v[4:5], v[4:5], v[8:9]
	s_nop 0
	v_pk_mul_f32 v[0:1], v[0:1], v[4:5]
	v_pk_fma_f32 v[4:5], v[6:7], v[74:75], v[64:65]
	v_cvt_pk_bf16_f32 v0, v0, v1
	v_mul_f32_e32 v1, 0xbfb8aa3b, v4
	v_exp_f32_e32 v1, v1
	s_nop 0
	v_add_f32_e32 v1, 1.0, v1
	v_rcp_f32_e32 v6, v1
	v_mul_f32_e32 v1, 0xbfb8aa3b, v5
	v_exp_f32_e32 v1, v1
	s_nop 0
	v_add_f32_e32 v1, 1.0, v1
	v_rcp_f32_e32 v7, v1
	s_nop 0
	v_pk_mul_f32 v[4:5], v[4:5], v[6:7]
	s_nop 0
	v_pk_mul_f32 v[2:3], v[2:3], v[4:5]
	s_nop 0
	v_cvt_pk_bf16_f32 v1, v2, v3
	v_lshl_add_u64 v[2:3], v[36:37], 0, s[18:19]
	v_lshl_add_u64 v[2:3], v[2:3], 0, v[198:199]
	ds_bpermute_b32 v228, v231, v0
	ds_bpermute_b32 v229, v231, v1
	v_lshl_add_u64 v[252:253], v[2:3], 0, v[250:251]
	s_waitcnt lgkmcnt(0)
	global_store_dwordx2 v[252:253], v[228:229], off
	s_cbranch_vccnz .LBB0_597

; template <int EPI> ...
;     ...
;     if (EPI == 0) {
; #pragma unroll
;       for (int bj = 0; bj < 2; ++bj) {
;         const int cbase = bcol + bj * 128 + wc * 32;
;         float4 swg = make_float4(0.f, 0.f, 0.f, 0.f), swu = swg;
;         if (swrow) { swg = *(const float4*)(swrow + cbase + fq * 4); swu = *(const float4*)(swrow + cbase + 16 + fq * 4); }
;         const float sg4[4] = {swg.x, swg.y, swg.z, swg.w}, su4[4] = {swu.x, swu.y, swu.z, swu.w};
; #pragma unroll
;         for (int m = 0; m < 4; ++m) {
;           float v[4];
; #pragma unroll
;           for (int j = 0; j < 4; ++j) {
;             float g = acc[ai][bj][m][0][j] * rs[m] + sg4[j];
;             float u = acc[ai][bj][m][1][j] * rs[m] + su4[j];
;             v[j] = g * __builtin_amdgcn_rcpf(1.f + __expf(-g)) * u;
;           }
;           uint2 o; o.x = pack2(v[0], v[1]); o.y = pack2(v[2], v[3]);
;           *(uint2*)(ea.out16 + (size_t)(rb + m * 16 + fr) * DFF + (cbase >> 1) + fq * 4) = o;
;         }
;       }
.LBB0_588:
	s_lshl_b32 s11, s11, 6
	v_or_b32_e32 v88, s10, v141
	v_add_u32_e32 v150, s11, v88
	s_waitcnt lgkmcnt(0)
	v_pk_fma_f32 v[88:89], v[128:129], v[146:147], v[132:133] op_sel_hi:[1,0,1]
	v_pk_fma_f32 v[124:125], v[124:125], v[146:147], v[136:137] op_sel_hi:[1,0,1]
	v_mul_f32_e32 v91, 0xbfb8aa3b, v88
	v_exp_f32_e32 v91, v91
	v_pk_fma_f32 v[120:121], v[120:121], v[144:145], v[132:133] op_sel_hi:[1,0,1]
	v_pk_fma_f32 v[126:127], v[126:127], v[146:147], v[138:139] op_sel_hi:[1,0,1]
	s_ashr_i32 s10, s21, 1
	v_add_f32_e32 v91, 1.0, v91
	v_rcp_f32_e32 v128, v91
	v_mul_f32_e32 v91, 0xbfb8aa3b, v89
	v_exp_f32_e32 v91, v91
	s_ashr_i32 s11, s10, 31
	s_lshl_b64 s[10:11], s[10:11], 1
	v_lshlrev_b32_e32 v198, 1, v149
	v_add_f32_e32 v91, 1.0, v91
	v_rcp_f32_e32 v129, v91
	v_pk_fma_f32 v[116:117], v[116:117], v[144:145], v[136:137] op_sel_hi:[1,0,1]
	v_pk_fma_f32 v[118:119], v[118:119], v[144:145], v[138:139] op_sel_hi:[1,0,1]
	v_pk_fma_f32 v[112:113], v[112:113], v[142:143], v[132:133] op_sel_hi:[1,0,1]
	v_pk_mul_f32 v[88:89], v[88:89], v[128:129]
	v_pk_fma_f32 v[108:109], v[108:109], v[142:143], v[136:137] op_sel_hi:[1,0,1]
	v_pk_mul_f32 v[88:89], v[124:125], v[88:89]
	v_pk_fma_f32 v[110:111], v[110:111], v[142:143], v[138:139] op_sel_hi:[1,0,1]
	v_cvt_pk_bf16_f32 v128, v88, v89
	v_pk_fma_f32 v[88:89], v[130:131], v[146:147], v[134:135] op_sel_hi:[1,0,1]
	v_pk_fma_f32 v[104:105], v[104:105], v[140:141], v[132:133] op_sel_hi:[1,0,1]
	v_mul_f32_e32 v91, 0xbfb8aa3b, v88
	v_exp_f32_e32 v91, v91
	v_pk_fma_f32 v[100:101], v[100:101], v[140:141], v[136:137] op_sel_hi:[1,0,1]
	v_pk_fma_f32 v[102:103], v[102:103], v[140:141], v[138:139] op_sel_hi:[1,0,1]
	s_andn2_b64 vcc, exec, s[18:19]
	v_add_f32_e32 v91, 1.0, v91
	v_rcp_f32_e32 v124, v91
	v_mul_f32_e32 v91, 0xbfb8aa3b, v89
	v_exp_f32_e32 v91, v91
	s_nop 0
	v_add_f32_e32 v91, 1.0, v91
	v_rcp_f32_e32 v125, v91
	v_mul_f32_e32 v91, 0xbfb8aa3b, v120
	v_exp_f32_e32 v91, v91
	v_pk_mul_f32 v[88:89], v[88:89], v[124:125]
	s_nop 0
	v_pk_mul_f32 v[88:89], v[126:127], v[88:89]
	v_add_f32_e32 v91, 1.0, v91
	v_cvt_pk_bf16_f32 v129, v88, v89
	v_mov_b64_e32 v[88:89], s[14:15]
	v_mad_i64_i32 v[124:125], s[24:25], v150, s60, v[88:89]
	v_lshl_add_u64 v[126:127], v[124:125], 0, s[10:11]
	v_lshl_add_u64 v[126:127], v[126:127], 0, v[198:199]
	ds_bpermute_b32 v228, v231, v128
	ds_bpermute_b32 v229, v231, v129
	v_lshl_add_u64 v[252:253], v[126:127], 0, v[250:251]
	s_waitcnt lgkmcnt(0)
	global_store_dwordx2 v[252:253], v[228:229], off
	v_rcp_f32_e32 v126, v91
	v_mul_f32_e32 v91, 0xbfb8aa3b, v121
	v_exp_f32_e32 v91, v91
	s_nop 0
	v_add_f32_e32 v91, 1.0, v91
	v_rcp_f32_e32 v127, v91
	s_nop 0
	v_pk_mul_f32 v[120:121], v[120:121], v[126:127]
	s_nop 0
	v_pk_mul_f32 v[116:117], v[116:117], v[120:121]
	s_nop 0
	v_cvt_pk_bf16_f32 v120, v116, v117
	v_pk_fma_f32 v[116:117], v[122:123], v[144:145], v[134:135] op_sel_hi:[1,0,1]
	s_nop 0
	v_mul_f32_e32 v91, 0xbfb8aa3b, v116
	v_exp_f32_e32 v91, v91
	s_nop 0
	v_add_f32_e32 v91, 1.0, v91
	v_rcp_f32_e32 v122, v91
	v_mul_f32_e32 v91, 0xbfb8aa3b, v117
	v_exp_f32_e32 v91, v91
	s_nop 0
	v_add_f32_e32 v91, 1.0, v91
	v_rcp_f32_e32 v123, v91
	v_or_b32_e32 v91, 16, v150
	v_pk_mul_f32 v[116:117], v[116:117], v[122:123]
	s_nop 0
	v_pk_mul_f32 v[116:117], v[118:119], v[116:117]
	s_nop 0
	v_cvt_pk_bf16_f32 v121, v116, v117
	v_mad_i64_i32 v[116:117], s[24:25], v91, s60, v[88:89]
	v_mul_f32_e32 v91, 0xbfb8aa3b, v112
	v_exp_f32_e32 v91, v91
	v_lshl_add_u64 v[118:119], v[116:117], 0, s[10:11]
	v_lshl_add_u64 v[118:119], v[118:119], 0, v[198:199]
	ds_bpermute_b32 v228, v231, v120
	ds_bpermute_b32 v229, v231, v121
	v_lshl_add_u64 v[252:253], v[118:119], 0, v[250:251]
	s_waitcnt lgkmcnt(0)
	global_store_dwordx2 v[252:253], v[228:229], off
	v_add_f32_e32 v91, 1.0, v91
	v_rcp_f32_e32 v118, v91
	v_mul_f32_e32 v91, 0xbfb8aa3b, v113
	v_exp_f32_e32 v91, v91
	s_nop 0
	v_add_f32_e32 v91, 1.0, v91
	v_rcp_f32_e32 v119, v91
	s_nop 0
	v_pk_mul_f32 v[112:113], v[112:113], v[118:119]
	s_nop 0
	v_pk_mul_f32 v[108:109], v[108:109], v[112:113]
	s_nop 0
	v_cvt_pk_bf16_f32 v112, v108, v109
	v_pk_fma_f32 v[108:109], v[114:115], v[142:143], v[134:135] op_sel_hi:[1,0,1]
	s_nop 0
	v_mul_f32_e32 v91, 0xbfb8aa3b, v108
	v_exp_f32_e32 v91, v91
	s_nop 0
	v_add_f32_e32 v91, 1.0, v91
	v_rcp_f32_e32 v114, v91
	v_mul_f32_e32 v91, 0xbfb8aa3b, v109
	v_exp_f32_e32 v91, v91
	s_nop 0
	v_add_f32_e32 v91, 1.0, v91
	v_rcp_f32_e32 v115, v91
	v_or_b32_e32 v91, 32, v150
	v_pk_mul_f32 v[108:109], v[108:109], v[114:115]
	s_nop 0
	v_pk_mul_f32 v[108:109], v[110:111], v[108:109]
	s_nop 0
	v_cvt_pk_bf16_f32 v113, v108, v109
	v_mad_i64_i32 v[108:109], s[24:25], v91, s60, v[88:89]
	v_mul_f32_e32 v91, 0xbfb8aa3b, v104
	v_exp_f32_e32 v91, v91
	v_lshl_add_u64 v[110:111], v[108:109], 0, s[10:11]
	v_lshl_add_u64 v[110:111], v[110:111], 0, v[198:199]
	ds_bpermute_b32 v228, v231, v112
	ds_bpermute_b32 v229, v231, v113
	v_lshl_add_u64 v[252:253], v[110:111], 0, v[250:251]
	s_waitcnt lgkmcnt(0)
	global_store_dwordx2 v[252:253], v[228:229], off
	v_add_f32_e32 v91, 1.0, v91
	v_rcp_f32_e32 v110, v91
	v_mul_f32_e32 v91, 0xbfb8aa3b, v105
	v_exp_f32_e32 v91, v91
	s_nop 0
	v_add_f32_e32 v91, 1.0, v91
	v_rcp_f32_e32 v111, v91
	s_nop 0
	v_pk_mul_f32 v[104:105], v[104:105], v[110:111]
	s_nop 0
	v_pk_mul_f32 v[100:101], v[100:101], v[104:105]
	v_pk_fma_f32 v[104:105], v[106:107], v[140:141], v[134:135] op_sel_hi:[1,0,1]
	v_cvt_pk_bf16_f32 v100, v100, v101
	v_mul_f32_e32 v91, 0xbfb8aa3b, v104
	v_exp_f32_e32 v91, v91
	s_nop 0
	v_add_f32_e32 v91, 1.0, v91
	v_rcp_f32_e32 v106, v91
	v_mul_f32_e32 v91, 0xbfb8aa3b, v105
	v_exp_f32_e32 v91, v91
	s_nop 0
	v_add_f32_e32 v91, 1.0, v91
	v_rcp_f32_e32 v107, v91
	v_or_b32_e32 v91, 48, v150
	v_pk_mul_f32 v[104:105], v[104:105], v[106:107]
	s_nop 0
	v_pk_mul_f32 v[102:103], v[102:103], v[104:105]
	v_mad_i64_i32 v[104:105], s[24:25], v91, s60, v[88:89]
	v_lshl_add_u64 v[88:89], v[104:105], 0, s[10:11]
	v_cvt_pk_bf16_f32 v101, v102, v103
	v_lshl_add_u64 v[88:89], v[88:89], 0, v[198:199]
	ds_bpermute_b32 v228, v231, v100
	ds_bpermute_b32 v229, v231, v101
	v_lshl_add_u64 v[252:253], v[88:89], 0, v[250:251]
	s_waitcnt lgkmcnt(0)
	global_store_dwordx2 v[252:253], v[228:229], off
	v_mov_b32_e32 v91, 0
	v_mov_b32_e32 v88, 0
	v_mov_b32_e32 v89, 0
	v_mov_b32_e32 v102, 0
	v_mov_b32_e32 v103, 0
	v_mov_b32_e32 v100, 0
	v_mov_b32_e32 v101, 0
	s_cbranch_vccnz .LBB0_590
	s_lshl_b32 s18, s21, 2
	s_add_i32 s18, s22, s18
	v_lshl_add_u32 v100, v149, 2, s18
	ds_read_b128 v[88:91], v100 offset:512
	ds_read_b128 v[100:103], v100 offset:576
; template <int EPI> ...
;     ...
;     if (EPI == 0) {
; #pragma unroll
;       for (int bj = 0; bj < 2; ++bj) {
;         const int cbase = bcol + bj * 128 + wc * 32;
;         float4 swg = make_float4(0.f, 0.f, 0.f, 0.f), swu = swg;
;         if (swrow) { swg = *(const float4*)(swrow + cbase + fq * 4); swu = *(const float4*)(swrow + cbase + 16 + fq * 4); }
;         const float sg4[4] = {swg.x, swg.y, swg.z, swg.w}, su4[4] = {swu.x, swu.y, swu.z, swu.w};
; #pragma unroll
;         for (int m = 0; m < 4; ++m) {
;           float v[4];
; #pragma unroll
;           for (int j = 0; j < 4; ++j) {
;             float g = acc[ai][bj][m][0][j] * rs[m] + sg4[j];
;             float u = acc[ai][bj][m][1][j] * rs[m] + su4[j];
;             v[j] = g * __builtin_amdgcn_rcpf(1.f + __expf(-g)) * u;
;           }
;           uint2 o; o.x = pack2(v[0], v[1]); o.y = pack2(v[2], v[3]);
;           *(uint2*)(ea.out16 + (size_t)(rb + m * 16 + fr) * DFF + (cbase >> 1) + fq * 4) = o;
;         }
;       }
.LBB0_590:
	v_mov_b32_e32 v147, v146
	s_waitcnt lgkmcnt(0)
	v_pk_fma_f32 v[96:97], v[96:97], v[146:147], v[88:89]
	v_pk_fma_f32 v[92:93], v[92:93], v[146:147], v[100:101]
	v_mul_f32_e32 v106, 0xbfb8aa3b, v96
	v_mul_f32_e32 v107, 0xbfb8aa3b, v97
	v_exp_f32_e32 v106, v106
	v_exp_f32_e32 v107, v107
	s_or_b32 s18, s21, 0x80
	s_ashr_i32 s18, s18, 1
	v_add_f32_e32 v106, 1.0, v106
	v_add_f32_e32 v107, 1.0, v107
	v_rcp_f32_e32 v106, v106
	v_rcp_f32_e32 v107, v107
	s_ashr_i32 s19, s18, 31
	v_pk_fma_f32 v[94:95], v[94:95], v[146:147], v[102:103]
	s_lshl_b64 s[18:19], s[18:19], 1
	v_pk_mul_f32 v[96:97], v[96:97], v[106:107]
	v_mov_b32_e32 v145, v144
	v_pk_mul_f32 v[92:93], v[92:93], v[96:97]
	v_pk_fma_f32 v[96:97], v[98:99], v[146:147], v[90:91]
	v_cvt_pk_bf16_f32 v92, v92, v93
	v_mul_f32_e32 v93, 0xbfb8aa3b, v96
	v_exp_f32_e32 v93, v93
	v_pk_fma_f32 v[84:85], v[84:85], v[144:145], v[88:89]
	v_pk_fma_f32 v[80:81], v[80:81], v[144:145], v[100:101]
	v_pk_fma_f32 v[82:83], v[82:83], v[144:145], v[102:103]
	v_add_f32_e32 v93, 1.0, v93
	v_rcp_f32_e32 v98, v93
	v_mul_f32_e32 v93, 0xbfb8aa3b, v97
	v_exp_f32_e32 v93, v93
	v_mov_b32_e32 v143, v142
	v_pk_fma_f32 v[76:77], v[76:77], v[142:143], v[88:89]
	v_pk_fma_f32 v[72:73], v[72:73], v[142:143], v[100:101]
	v_add_f32_e32 v93, 1.0, v93
	v_rcp_f32_e32 v99, v93
	v_pk_fma_f32 v[74:75], v[74:75], v[142:143], v[102:103]
	v_mov_b32_e32 v141, v140
	v_pk_fma_f32 v[68:69], v[68:69], v[140:141], v[88:89]
	v_pk_mul_f32 v[96:97], v[96:97], v[98:99]
	v_pk_fma_f32 v[64:65], v[64:65], v[140:141], v[100:101]
	v_pk_mul_f32 v[94:95], v[94:95], v[96:97]
	v_pk_fma_f32 v[66:67], v[66:67], v[140:141], v[102:103]
	v_cvt_pk_bf16_f32 v93, v94, v95
	v_lshl_add_u64 v[94:95], v[124:125], 0, s[18:19]
	v_lshl_add_u64 v[94:95], v[94:95], 0, v[198:199]
	ds_bpermute_b32 v228, v231, v92
	ds_bpermute_b32 v229, v231, v93
	v_lshl_add_u64 v[252:253], v[94:95], 0, v[250:251]
	s_waitcnt lgkmcnt(0)
	global_store_dwordx2 v[252:253], v[228:229], off
	v_mul_f32_e32 v92, 0xbfb8aa3b, v84
	v_mul_f32_e32 v93, 0xbfb8aa3b, v85
	v_exp_f32_e32 v92, v92
	v_exp_f32_e32 v93, v93
	s_and_b64 vcc, exec, s[6:7]
	v_add_f32_e32 v92, 1.0, v92
	v_add_f32_e32 v93, 1.0, v93
	v_rcp_f32_e32 v92, v92
	v_rcp_f32_e32 v93, v93
	s_nop 0
	v_pk_mul_f32 v[84:85], v[84:85], v[92:93]
	s_nop 0
	v_pk_mul_f32 v[80:81], v[80:81], v[84:85]
	v_pk_fma_f32 v[84:85], v[86:87], v[144:145], v[90:91]
	v_cvt_pk_bf16_f32 v80, v80, v81
	v_mul_f32_e32 v81, 0xbfb8aa3b, v84
	v_exp_f32_e32 v81, v81
	s_nop 0
	v_add_f32_e32 v81, 1.0, v81
	v_rcp_f32_e32 v86, v81
	v_mul_f32_e32 v81, 0xbfb8aa3b, v85
	v_exp_f32_e32 v81, v81
	s_nop 0
	v_add_f32_e32 v81, 1.0, v81
	v_rcp_f32_e32 v87, v81
	s_nop 0
	v_pk_mul_f32 v[84:85], v[84:85], v[86:87]
	s_nop 0
	v_pk_mul_f32 v[82:83], v[82:83], v[84:85]
	s_nop 0
	v_cvt_pk_bf16_f32 v81, v82, v83
	v_lshl_add_u64 v[82:83], v[116:117], 0, s[18:19]
	v_lshl_add_u64 v[82:83], v[82:83], 0, v[198:199]
	ds_bpermute_b32 v228, v231, v80
	ds_bpermute_b32 v229, v231, v81
	v_lshl_add_u64 v[252:253], v[82:83], 0, v[250:251]
	s_waitcnt lgkmcnt(0)
	global_store_dwordx2 v[252:253], v[228:229], off
	v_mul_f32_e32 v80, 0xbfb8aa3b, v76
	v_mul_f32_e32 v81, 0xbfb8aa3b, v77
	v_exp_f32_e32 v80, v80
	v_exp_f32_e32 v81, v81
	v_add_f32_e32 v80, 1.0, v80
	v_add_f32_e32 v81, 1.0, v81
	v_rcp_f32_e32 v80, v80
	v_rcp_f32_e32 v81, v81
	s_nop 0
	v_pk_mul_f32 v[76:77], v[76:77], v[80:81]
	s_nop 0
	v_pk_mul_f32 v[72:73], v[72:73], v[76:77]
	v_pk_fma_f32 v[76:77], v[78:79], v[142:143], v[90:91]
	v_cvt_pk_bf16_f32 v72, v72, v73
	v_mul_f32_e32 v73, 0xbfb8aa3b, v76
	v_exp_f32_e32 v73, v73
	s_nop 0
	v_add_f32_e32 v73, 1.0, v73
	v_rcp_f32_e32 v78, v73
	v_mul_f32_e32 v73, 0xbfb8aa3b, v77
	v_exp_f32_e32 v73, v73
	s_nop 0
	v_add_f32_e32 v73, 1.0, v73
	v_rcp_f32_e32 v79, v73
	s_nop 0
	v_pk_mul_f32 v[76:77], v[76:77], v[78:79]
	s_nop 0
	v_pk_mul_f32 v[74:75], v[74:75], v[76:77]
	s_nop 0
	v_cvt_pk_bf16_f32 v73, v74, v75
	v_lshl_add_u64 v[74:75], v[108:109], 0, s[18:19]
	v_lshl_add_u64 v[74:75], v[74:75], 0, v[198:199]
	ds_bpermute_b32 v228, v231, v72
	ds_bpermute_b32 v229, v231, v73
	v_lshl_add_u64 v[252:253], v[74:75], 0, v[250:251]
	s_waitcnt lgkmcnt(0)
	global_store_dwordx2 v[252:253], v[228:229], off
	v_mul_f32_e32 v72, 0xbfb8aa3b, v68
	v_mul_f32_e32 v73, 0xbfb8aa3b, v69
	v_exp_f32_e32 v72, v72
	v_exp_f32_e32 v73, v73
	v_add_f32_e32 v72, 1.0, v72
	v_add_f32_e32 v73, 1.0, v73
	v_rcp_f32_e32 v72, v72
	v_rcp_f32_e32 v73, v73
	s_nop 0
	v_pk_mul_f32 v[68:69], v[68:69], v[72:73]
	s_nop 0
	v_pk_mul_f32 v[64:65], v[64:65], v[68:69]
	v_pk_fma_f32 v[68:69], v[70:71], v[140:141], v[90:91]
	v_cvt_pk_bf16_f32 v64, v64, v65
	v_mul_f32_e32 v65, 0xbfb8aa3b, v68
	v_exp_f32_e32 v65, v65
	s_nop 0
	v_add_f32_e32 v65, 1.0, v65
	v_rcp_f32_e32 v70, v65
	v_mul_f32_e32 v65, 0xbfb8aa3b, v69
	v_exp_f32_e32 v65, v65
	s_nop 0
	v_add_f32_e32 v65, 1.0, v65
	v_rcp_f32_e32 v71, v65
	s_nop 0
	v_pk_mul_f32 v[68:69], v[68:69], v[70:71]
	s_nop 0
	v_pk_mul_f32 v[66:67], v[66:67], v[68:69]
	s_nop 0
	v_cvt_pk_bf16_f32 v65, v66, v67
	v_lshl_add_u64 v[66:67], v[104:105], 0, s[18:19]
	v_lshl_add_u64 v[66:67], v[66:67], 0, v[198:199]
	ds_bpermute_b32 v228, v231, v64
	ds_bpermute_b32 v229, v231, v65
	v_lshl_add_u64 v[252:253], v[66:67], 0, v[250:251]
	s_waitcnt lgkmcnt(0)
	global_store_dwordx2 v[252:253], v[228:229], off
	s_cbranch_vccnz .LBB0_592
	ds_read2_b32 v[76:77], v151 offset0:160 offset1:176
	ds_read2_b32 v[80:81], v151 offset0:128 offset1:144
	s_waitcnt lgkmcnt(0)
	v_mov_b32_e32 v74, v77
	v_mov_b32_e32 v78, v81
	s_branch .LBB0_593

; template <int EPI> ...
;     ...
;     if (EPI == 0) {
; #pragma unroll
;       for (int bj = 0; bj < 2; ++bj) {
;         const int cbase = bcol + bj * 128 + wc * 32;
;         float4 swg = make_float4(0.f, 0.f, 0.f, 0.f), swu = swg;
;         if (swrow) { swg = *(const float4*)(swrow + cbase + fq * 4); swu = *(const float4*)(swrow + cbase + 16 + fq * 4); }
;         const float sg4[4] = {swg.x, swg.y, swg.z, swg.w}, su4[4] = {swu.x, swu.y, swu.z, swu.w};
; #pragma unroll
;         for (int m = 0; m < 4; ++m) {
;           float v[4];
; #pragma unroll
;           for (int j = 0; j < 4; ++j) {
;             float g = acc[ai][bj][m][0][j] * rs[m] + sg4[j];
;             float u = acc[ai][bj][m][1][j] * rs[m] + su4[j];
;             v[j] = g * __builtin_amdgcn_rcpf(1.f + __expf(-g)) * u;
;           }
;           uint2 o; o.x = pack2(v[0], v[1]); o.y = pack2(v[2], v[3]);
;           *(uint2*)(ea.out16 + (size_t)(rb + m * 16 + fr) * DFF + (cbase >> 1) + fq * 4) = o;
;         }
;       }
.LBB0_595:
	s_waitcnt lgkmcnt(0)
	v_pk_fma_f32 v[60:61], v[60:61], v[80:81], v[66:67] op_sel_hi:[1,0,1]
	v_pk_fma_f32 v[56:57], v[56:57], v[80:81], v[70:71] op_sel_hi:[1,0,1]
	v_mul_f32_e32 v75, 0xbfb8aa3b, v60
	v_exp_f32_e32 v75, v75
	v_pk_fma_f32 v[58:59], v[58:59], v[80:81], v[72:73] op_sel_hi:[1,0,1]
	v_add_u32_e32 v65, 0x80, v150
	v_pk_fma_f32 v[52:53], v[52:53], v[78:79], v[66:67] op_sel_hi:[1,0,1]
	v_add_f32_e32 v75, 1.0, v75
	v_rcp_f32_e32 v82, v75
	v_mul_f32_e32 v75, 0xbfb8aa3b, v61
	v_exp_f32_e32 v75, v75
	v_pk_fma_f32 v[48:49], v[48:49], v[78:79], v[70:71] op_sel_hi:[1,0,1]
	v_pk_fma_f32 v[50:51], v[50:51], v[78:79], v[72:73] op_sel_hi:[1,0,1]
	v_pk_fma_f32 v[44:45], v[44:45], v[76:77], v[66:67] op_sel_hi:[1,0,1]
	v_add_f32_e32 v75, 1.0, v75
	v_rcp_f32_e32 v83, v75
	v_pk_fma_f32 v[40:41], v[40:41], v[76:77], v[70:71] op_sel_hi:[1,0,1]
	v_pk_fma_f32 v[42:43], v[42:43], v[76:77], v[72:73] op_sel_hi:[1,0,1]
	v_pk_fma_f32 v[36:37], v[36:37], v[74:75], v[66:67] op_sel_hi:[1,0,1]
	v_pk_mul_f32 v[60:61], v[60:61], v[82:83]
	v_pk_fma_f32 v[32:33], v[32:33], v[74:75], v[70:71] op_sel_hi:[1,0,1]
	v_pk_mul_f32 v[56:57], v[56:57], v[60:61]
	v_pk_fma_f32 v[34:35], v[34:35], v[74:75], v[72:73] op_sel_hi:[1,0,1]
	v_cvt_pk_bf16_f32 v60, v56, v57
	v_pk_fma_f32 v[56:57], v[62:63], v[80:81], v[68:69] op_sel_hi:[1,0,1]
	s_andn2_b64 vcc, exec, s[6:7]
	v_mul_f32_e32 v61, 0xbfb8aa3b, v56
	v_exp_f32_e32 v61, v61
	s_nop 0
	v_add_f32_e32 v61, 1.0, v61
	v_rcp_f32_e32 v62, v61
	v_mul_f32_e32 v61, 0xbfb8aa3b, v57
	v_exp_f32_e32 v61, v61
	s_nop 0
	v_add_f32_e32 v61, 1.0, v61
	v_rcp_f32_e32 v63, v61
	s_nop 0
	v_pk_mul_f32 v[56:57], v[56:57], v[62:63]
	s_nop 0
	v_pk_mul_f32 v[56:57], v[58:59], v[56:57]
	v_mov_b64_e32 v[58:59], s[14:15]
	v_cvt_pk_bf16_f32 v61, v56, v57
	v_mad_i64_i32 v[56:57], s[22:23], v65, s60, v[58:59]
	v_lshl_add_u64 v[62:63], v[56:57], 0, s[10:11]
	v_lshl_add_u64 v[62:63], v[62:63], 0, v[198:199]
	ds_bpermute_b32 v228, v231, v60
	ds_bpermute_b32 v229, v231, v61
	v_lshl_add_u64 v[252:253], v[62:63], 0, v[250:251]
	s_waitcnt lgkmcnt(0)
	global_store_dwordx2 v[252:253], v[228:229], off
	v_mul_f32_e32 v60, 0xbfb8aa3b, v52
	v_mul_f32_e32 v61, 0xbfb8aa3b, v53
	v_exp_f32_e32 v60, v60
	v_exp_f32_e32 v61, v61
	v_mov_b32_e32 v65, 0
	v_mov_b32_e32 v62, 0
	v_add_f32_e32 v60, 1.0, v60
	v_add_f32_e32 v61, 1.0, v61
	v_rcp_f32_e32 v60, v60
	v_rcp_f32_e32 v61, v61
	v_mov_b32_e32 v63, 0
	v_pk_mul_f32 v[52:53], v[52:53], v[60:61]
	s_nop 0
	v_pk_mul_f32 v[48:49], v[48:49], v[52:53]
	s_nop 0
	v_cvt_pk_bf16_f32 v52, v48, v49
	v_pk_fma_f32 v[48:49], v[54:55], v[78:79], v[68:69] op_sel_hi:[1,0,1]
	s_nop 0
	v_mul_f32_e32 v53, 0xbfb8aa3b, v48
	v_exp_f32_e32 v53, v53
	s_nop 0
	v_add_f32_e32 v53, 1.0, v53
	v_rcp_f32_e32 v54, v53
	v_mul_f32_e32 v53, 0xbfb8aa3b, v49
	v_exp_f32_e32 v53, v53
	s_nop 0
	v_add_f32_e32 v53, 1.0, v53
	v_rcp_f32_e32 v55, v53
	s_nop 0
	v_pk_mul_f32 v[48:49], v[48:49], v[54:55]
	s_nop 0
	v_pk_mul_f32 v[48:49], v[50:51], v[48:49]
	s_nop 0
	v_cvt_pk_bf16_f32 v53, v48, v49
	v_add_u32_e32 v48, 0x90, v150
	v_mad_i64_i32 v[48:49], s[22:23], v48, s60, v[58:59]
	v_lshl_add_u64 v[50:51], v[48:49], 0, s[10:11]
	v_lshl_add_u64 v[50:51], v[50:51], 0, v[198:199]
	ds_bpermute_b32 v228, v231, v52
	ds_bpermute_b32 v229, v231, v53
	v_lshl_add_u64 v[252:253], v[50:51], 0, v[250:251]
	s_waitcnt lgkmcnt(0)
	global_store_dwordx2 v[252:253], v[228:229], off
	v_mul_f32_e32 v50, 0xbfb8aa3b, v44
	v_mul_f32_e32 v51, 0xbfb8aa3b, v45
	v_exp_f32_e32 v50, v50
	v_exp_f32_e32 v51, v51
	v_add_f32_e32 v50, 1.0, v50
	v_add_f32_e32 v51, 1.0, v51
	v_rcp_f32_e32 v50, v50
	v_rcp_f32_e32 v51, v51
	s_nop 0
	v_pk_mul_f32 v[44:45], v[44:45], v[50:51]
	s_nop 0
	v_pk_mul_f32 v[40:41], v[40:41], v[44:45]
	s_nop 0
	v_cvt_pk_bf16_f32 v44, v40, v41
	v_pk_fma_f32 v[40:41], v[46:47], v[76:77], v[68:69] op_sel_hi:[1,0,1]
	s_nop 0
	v_mul_f32_e32 v45, 0xbfb8aa3b, v40
	v_exp_f32_e32 v45, v45
	s_nop 0
	v_add_f32_e32 v45, 1.0, v45
	v_rcp_f32_e32 v46, v45
	v_mul_f32_e32 v45, 0xbfb8aa3b, v41
	v_exp_f32_e32 v45, v45
	s_nop 0
	v_add_f32_e32 v45, 1.0, v45
	v_rcp_f32_e32 v47, v45
	s_nop 0
	v_pk_mul_f32 v[40:41], v[40:41], v[46:47]
	s_nop 0
	v_pk_mul_f32 v[40:41], v[42:43], v[40:41]
	s_nop 0
	v_cvt_pk_bf16_f32 v45, v40, v41
	v_add_u32_e32 v40, 0xa0, v150
	v_mad_i64_i32 v[40:41], s[22:23], v40, s60, v[58:59]
	v_lshl_add_u64 v[42:43], v[40:41], 0, s[10:11]
	v_lshl_add_u64 v[42:43], v[42:43], 0, v[198:199]
	ds_bpermute_b32 v228, v231, v44
	ds_bpermute_b32 v229, v231, v45
	v_lshl_add_u64 v[252:253], v[42:43], 0, v[250:251]
	s_waitcnt lgkmcnt(0)
	global_store_dwordx2 v[252:253], v[228:229], off
	v_mul_f32_e32 v42, 0xbfb8aa3b, v36
	v_mul_f32_e32 v43, 0xbfb8aa3b, v37
	v_exp_f32_e32 v42, v42
	v_exp_f32_e32 v43, v43
	v_add_f32_e32 v42, 1.0, v42
	v_add_f32_e32 v43, 1.0, v43
	v_rcp_f32_e32 v42, v42
	v_rcp_f32_e32 v43, v43
	s_nop 0
	v_pk_mul_f32 v[36:37], v[36:37], v[42:43]
	s_nop 0
	v_pk_mul_f32 v[32:33], v[32:33], v[36:37]
	v_pk_fma_f32 v[36:37], v[38:39], v[74:75], v[68:69] op_sel_hi:[1,0,1]
	v_cvt_pk_bf16_f32 v32, v32, v33
	v_mul_f32_e32 v33, 0xbfb8aa3b, v36
	v_exp_f32_e32 v33, v33
	s_nop 0
	v_add_f32_e32 v33, 1.0, v33
	v_rcp_f32_e32 v38, v33
	v_mul_f32_e32 v33, 0xbfb8aa3b, v37
	v_exp_f32_e32 v33, v33
	s_nop 0
	v_add_f32_e32 v33, 1.0, v33
	v_rcp_f32_e32 v39, v33
	s_nop 0
	v_pk_mul_f32 v[36:37], v[36:37], v[38:39]
	s_nop 0
	v_pk_mul_f32 v[34:35], v[34:35], v[36:37]
	s_nop 0
	v_cvt_pk_bf16_f32 v33, v34, v35
	v_add_u32_e32 v34, 0xb0, v150
	v_mad_i64_i32 v[36:37], s[22:23], v34, s60, v[58:59]
	v_lshl_add_u64 v[34:35], v[36:37], 0, s[10:11]
	v_lshl_add_u64 v[34:35], v[34:35], 0, v[198:199]
	ds_bpermute_b32 v228, v231, v32
	ds_bpermute_b32 v229, v231, v33
	v_lshl_add_u64 v[252:253], v[34:35], 0, v[250:251]
	s_waitcnt lgkmcnt(0)
	global_store_dwordx2 v[252:253], v[228:229], off
	v_mov_b32_e32 v34, 0
	v_mov_b32_e32 v35, 0
	v_mov_b32_e32 v32, 0
	v_mov_b32_e32 v33, 0
	s_cbranch_vccnz .LBB0_555
	s_lshl_b32 s6, s21, 2
	s_add_i32 s6, s20, s6
	v_lshl_add_u32 v32, v149, 2, s6
	ds_read_b128 v[62:65], v32 offset:512
	ds_read_b128 v[32:35], v32 offset:576
	s_branch .LBB0_555
